# SwiGLU epilogue (P3,P7): 8 serial ssq load->vmcnt(0) round trips hoisted to one batch with counted vmcnt waits
# speedup vs baseline: 1.0008x; 1.0008x over previous
.LBB0_479:
	v_lshl_add_u32 v142, s36, 8, v148
	v_ashrrev_i32_e32 v143, 31, v142
	v_lshl_add_u64 v[146:147], v[142:143], 2, s[4:5]
	global_load_dword v241, v[146:147], off
	global_load_dword v242, v[146:147], off offset:64
	global_load_dword v243, v[146:147], off offset:128
	global_load_dword v244, v[146:147], off offset:192
	global_load_dword v245, v[146:147], off offset:512
	global_load_dword v246, v[146:147], off offset:576
	global_load_dword v247, v[146:147], off offset:640
	global_load_dword v248, v[146:147], off offset:704
	v_mov_b32_e32 v168, v125
	v_mov_b32_e32 v160, v127
	v_mov_b32_e32 v158, v118
	v_mov_b32_e32 v162, v129
	v_lshl_or_b32 v156, s22, 7, v150
	v_mov_b64_e32 v[144:145], s[6:7]
	v_ashrrev_i32_e32 v157, 31, v156
	v_or_b32_e32 v172, 16, v142
	v_mov_b32_e32 v164, v122
	v_mov_b32_e32 v166, v123
	v_mad_i64_i32 v[170:171], s[2:3], v142, s60, v[144:145]
	v_lshlrev_b64 v[122:123], 1, v[156:157]
	v_ashrrev_i32_e32 v173, 31, v172
	v_lshl_add_u64 v[156:157], v[170:171], 0, v[122:123]
	v_lshl_add_u64 v[170:171], v[172:173], 2, s[4:5]
	s_andn2_b64 vcc, exec, s[38:39]
	s_waitcnt vmcnt(7)
	v_mov_b32_e32 v143, v241
	v_fmamk_f32 v125, v143, 0x39800000, v155
	v_rsq_f32_e32 v125, v125
	s_nop 0
	v_mul_f32_e32 v127, 0xbfb8aa3b, v125
	v_mul_f32_e32 v118, v118, v127
	v_mul_f32_e32 v159, v125, v125
	v_mul_f32_e32 v125, v119, v127
	v_mul_f32_e32 v129, v120, v127
	v_mul_f32_e32 v143, v121, v127
	v_mul_f32_e32 v161, v114, v127
	v_mul_f32_e32 v163, v115, v127
	v_mul_f32_e32 v165, v116, v127
	v_mul_f32_e32 v127, v117, v127
	v_exp_f32_e32 v118, v118
	v_exp_f32_e32 v125, v125
	v_exp_f32_e32 v127, v127
	v_exp_f32_e32 v129, v129
	v_exp_f32_e32 v161, v161
	v_exp_f32_e32 v143, v143
	v_exp_f32_e32 v163, v163
	v_add_f32_e32 v118, 1.0, v118
	v_exp_f32_e32 v165, v165
	v_add_f32_e32 v125, 1.0, v125
	v_add_f32_e32 v174, 1.0, v127
	v_rcp_f32_e32 v127, v118
	v_add_f32_e32 v129, 1.0, v129
	v_add_f32_e32 v167, 1.0, v161
	v_rcp_f32_e32 v161, v125
	v_add_f32_e32 v143, 1.0, v143
	v_rcp_f32_e32 v129, v129
	v_add_f32_e32 v169, 1.0, v163
	v_rcp_f32_e32 v163, v143
	v_add_f32_e32 v173, 1.0, v165
	v_rcp_f32_e32 v165, v167
	v_pk_mul_f32 v[126:127], v[158:159], v[126:127]
	v_mov_b32_e32 v158, v119
	v_rcp_f32_e32 v167, v169
	v_pk_mul_f32 v[118:119], v[158:159], v[160:161]
	v_mov_b32_e32 v158, v120
	v_rcp_f32_e32 v125, v173
	v_mul_f32_e32 v120, v118, v119
	v_pk_mul_f32 v[118:119], v[158:159], v[128:129]
	v_mov_b32_e32 v158, v121
	v_rcp_f32_e32 v169, v174
	v_mul_f32_e32 v121, v118, v119
	v_pk_mul_f32 v[118:119], v[158:159], v[162:163]
	v_mov_b32_e32 v158, v114
	v_mul_f32_e32 v126, v126, v127
	v_cvt_pk_bf16_f32 v114, v126, v120
	v_mul_f32_e32 v120, v118, v119
	v_pk_mul_f32 v[118:119], v[158:159], v[164:165]
	v_mov_b32_e32 v158, v115
	v_mul_f32_e32 v126, v118, v119
	v_pk_mul_f32 v[118:119], v[158:159], v[166:167]
	v_mov_b32_e32 v158, v116
	v_mul_f32_e32 v116, v118, v119
	v_pk_mul_f32 v[118:119], v[158:159], v[124:125]
	v_mov_b32_e32 v158, v117
	v_mul_f32_e32 v117, v118, v119
	v_pk_mul_f32 v[118:119], v[158:159], v[168:169]
	v_cvt_pk_bf16_f32 v115, v121, v120
	v_cvt_pk_bf16_f32 v116, v126, v116
	v_mov_b32_e32 v120, v107
	v_mul_f32_e32 v118, v118, v119
	v_cvt_pk_bf16_f32 v117, v117, v118
	global_store_dwordx4 v[156:157], v[114:117], off
	s_nop 0
	v_mov_b32_e32 v124, v109
	v_mov_b32_e32 v114, v102
	v_mov_b32_e32 v116, v111
	v_mov_b32_e32 v118, v113
	v_or_b32_e32 v126, 32, v142
	v_ashrrev_i32_e32 v127, 31, v126
	v_lshl_add_u64 v[156:157], v[126:127], 2, s[4:5]
	v_mad_i64_i32 v[128:129], s[2:3], v172, s60, v[144:145]
	v_lshl_add_u64 v[128:129], v[128:129], 0, v[122:123]
	s_waitcnt vmcnt(7)
	v_mov_b32_e32 v115, v242
	v_fmamk_f32 v107, v115, 0x39800000, v155
	v_rsq_f32_e32 v107, v107
	s_nop 0
	v_mul_f32_e32 v109, 0xbfb8aa3b, v107
	v_mul_f32_e32 v102, v102, v109
	v_mul_f32_e32 v115, v107, v107
	v_mul_f32_e32 v107, v103, v109
	v_mul_f32_e32 v111, v104, v109
	v_exp_f32_e32 v102, v102
	v_mul_f32_e32 v117, v98, v109
	v_exp_f32_e32 v107, v107
	v_exp_f32_e32 v111, v111
	v_mul_f32_e32 v113, v105, v109
	v_exp_f32_e32 v117, v117
	v_mul_f32_e32 v119, v99, v109
	v_exp_f32_e32 v113, v113
	v_exp_f32_e32 v119, v119
	v_add_f32_e32 v102, 1.0, v102
	v_mul_f32_e32 v121, v100, v109
	v_add_f32_e32 v107, 1.0, v107
	v_add_f32_e32 v125, 1.0, v111
	v_rcp_f32_e32 v111, v102
	v_mul_f32_e32 v109, v101, v109
	v_exp_f32_e32 v121, v121
	v_add_f32_e32 v143, 1.0, v117
	v_rcp_f32_e32 v117, v107
	v_exp_f32_e32 v109, v109
	v_add_f32_e32 v127, 1.0, v113
	v_rcp_f32_e32 v113, v125
	v_add_f32_e32 v158, 1.0, v119
	v_rcp_f32_e32 v119, v127
	v_rcp_f32_e32 v107, v143
	v_pk_mul_f32 v[110:111], v[114:115], v[110:111]
	v_mov_b32_e32 v114, v103
	v_add_f32_e32 v159, 1.0, v121
	v_rcp_f32_e32 v121, v158
	v_pk_mul_f32 v[102:103], v[114:115], v[116:117]
	v_mov_b32_e32 v114, v104
	v_add_f32_e32 v160, 1.0, v109
	v_rcp_f32_e32 v109, v159
	v_mul_f32_e32 v104, v102, v103
	v_pk_mul_f32 v[102:103], v[114:115], v[112:113]
	v_mov_b32_e32 v114, v105
	v_rcp_f32_e32 v125, v160
	v_mul_f32_e32 v105, v102, v103
	v_pk_mul_f32 v[102:103], v[114:115], v[118:119]
	v_mov_b32_e32 v114, v98
	v_mul_f32_e32 v110, v110, v111
	v_cvt_pk_bf16_f32 v98, v110, v104
	v_mul_f32_e32 v104, v102, v103
	v_pk_mul_f32 v[102:103], v[114:115], v[106:107]
	v_mov_b32_e32 v114, v99
	v_mul_f32_e32 v106, v102, v103
	v_pk_mul_f32 v[102:103], v[114:115], v[120:121]
	v_mov_b32_e32 v114, v100
	v_mul_f32_e32 v100, v102, v103
	v_pk_mul_f32 v[102:103], v[114:115], v[108:109]
	v_mov_b32_e32 v114, v101
	v_mul_f32_e32 v101, v102, v103
	v_pk_mul_f32 v[102:103], v[114:115], v[124:125]
	v_cvt_pk_bf16_f32 v99, v105, v104
	v_cvt_pk_bf16_f32 v100, v106, v100
	v_mov_b32_e32 v104, v91
	v_mul_f32_e32 v102, v102, v103
	v_cvt_pk_bf16_f32 v101, v101, v102
	global_store_dwordx4 v[128:129], v[98:101], off
	s_nop 0
	v_mov_b32_e32 v106, v93
	v_mov_b32_e32 v98, v86
	v_mov_b32_e32 v100, v95
	v_mov_b32_e32 v102, v97
	v_or_b32_e32 v108, 48, v142
	v_ashrrev_i32_e32 v109, 31, v108
	v_lshl_add_u64 v[112:113], v[108:109], 2, s[4:5]
	v_mad_i64_i32 v[110:111], s[2:3], v126, s60, v[144:145]
	v_lshl_add_u64 v[110:111], v[110:111], 0, v[122:123]
	s_waitcnt vmcnt(7)
	v_mov_b32_e32 v99, v243
	v_fmamk_f32 v91, v99, 0x39800000, v155
	v_rsq_f32_e32 v91, v91
	s_nop 0
	v_mul_f32_e32 v93, 0xbfb8aa3b, v91
	v_mul_f32_e32 v86, v86, v93
	v_mul_f32_e32 v99, v91, v91
	v_mul_f32_e32 v91, v87, v93
	v_mul_f32_e32 v95, v88, v93
	v_exp_f32_e32 v86, v86
	v_mul_f32_e32 v101, v82, v93
	v_exp_f32_e32 v91, v91
	v_exp_f32_e32 v95, v95
	v_mul_f32_e32 v97, v89, v93
	v_exp_f32_e32 v101, v101
	v_mul_f32_e32 v103, v83, v93
	v_exp_f32_e32 v97, v97
	v_exp_f32_e32 v103, v103
	v_add_f32_e32 v86, 1.0, v86
	v_mul_f32_e32 v105, v84, v93
	v_add_f32_e32 v91, 1.0, v91
	v_add_f32_e32 v107, 1.0, v95
	v_rcp_f32_e32 v95, v86
	v_mul_f32_e32 v93, v85, v93
	v_exp_f32_e32 v105, v105
	v_add_f32_e32 v114, 1.0, v101
	v_rcp_f32_e32 v101, v91
	v_exp_f32_e32 v93, v93
	v_add_f32_e32 v109, 1.0, v97
	v_rcp_f32_e32 v97, v107
	v_add_f32_e32 v115, 1.0, v103
	v_rcp_f32_e32 v103, v109
	v_rcp_f32_e32 v91, v114
	v_pk_mul_f32 v[94:95], v[98:99], v[94:95]
	v_mov_b32_e32 v98, v87
	v_add_f32_e32 v116, 1.0, v105
	v_rcp_f32_e32 v105, v115
	v_pk_mul_f32 v[86:87], v[98:99], v[100:101]
	v_mov_b32_e32 v98, v88
	v_add_f32_e32 v117, 1.0, v93
	v_rcp_f32_e32 v93, v116
	v_mul_f32_e32 v88, v86, v87
	v_pk_mul_f32 v[86:87], v[98:99], v[96:97]
	v_mov_b32_e32 v98, v89
	v_rcp_f32_e32 v107, v117
	v_mul_f32_e32 v89, v86, v87
	v_pk_mul_f32 v[86:87], v[98:99], v[102:103]
	v_mov_b32_e32 v98, v82
	v_mul_f32_e32 v94, v94, v95
	v_cvt_pk_bf16_f32 v82, v94, v88
	v_mul_f32_e32 v88, v86, v87
	v_pk_mul_f32 v[86:87], v[98:99], v[90:91]
	v_mov_b32_e32 v98, v83
	v_mul_f32_e32 v90, v86, v87
	v_pk_mul_f32 v[86:87], v[98:99], v[104:105]
	v_mov_b32_e32 v98, v84
	v_mul_f32_e32 v84, v86, v87
	v_pk_mul_f32 v[86:87], v[98:99], v[92:93]
	v_mov_b32_e32 v98, v85
	v_mul_f32_e32 v85, v86, v87
	v_pk_mul_f32 v[86:87], v[98:99], v[106:107]
	v_cvt_pk_bf16_f32 v83, v89, v88
	v_cvt_pk_bf16_f32 v84, v90, v84
	v_mov_b32_e32 v88, v75
	v_mul_f32_e32 v86, v86, v87
	v_cvt_pk_bf16_f32 v85, v85, v86
	global_store_dwordx4 v[110:111], v[82:85], off
	s_nop 0
	v_mov_b32_e32 v90, v77
	v_mov_b32_e32 v82, v70
	v_mov_b32_e32 v84, v79
	v_mov_b32_e32 v86, v81
	v_mad_i64_i32 v[92:93], s[2:3], v108, s60, v[144:145]
	v_lshl_add_u64 v[92:93], v[92:93], 0, v[122:123]
	s_waitcnt vmcnt(7)
	v_mov_b32_e32 v83, v244
	v_fmamk_f32 v75, v83, 0x39800000, v155
	v_rsq_f32_e32 v75, v75
	s_nop 0
	v_mul_f32_e32 v77, 0xbfb8aa3b, v75
	v_mul_f32_e32 v70, v70, v77
	v_mul_f32_e32 v83, v75, v75
	v_mul_f32_e32 v75, v71, v77
	v_mul_f32_e32 v79, v72, v77
	v_exp_f32_e32 v70, v70
	v_mul_f32_e32 v85, v66, v77
	v_exp_f32_e32 v75, v75
	v_exp_f32_e32 v79, v79
	v_mul_f32_e32 v81, v73, v77
	v_exp_f32_e32 v85, v85
	v_mul_f32_e32 v87, v67, v77
	v_exp_f32_e32 v81, v81
	v_exp_f32_e32 v87, v87
	v_add_f32_e32 v70, 1.0, v70
	v_mul_f32_e32 v89, v68, v77
	v_add_f32_e32 v75, 1.0, v75
	v_add_f32_e32 v91, 1.0, v79
	v_rcp_f32_e32 v79, v70
	v_mul_f32_e32 v77, v69, v77
	v_exp_f32_e32 v89, v89
	v_add_f32_e32 v95, 1.0, v85
	v_rcp_f32_e32 v85, v75
	v_exp_f32_e32 v77, v77
	v_add_f32_e32 v94, 1.0, v81
	v_rcp_f32_e32 v81, v91
	v_add_f32_e32 v96, 1.0, v87
	v_rcp_f32_e32 v87, v94
	v_rcp_f32_e32 v75, v95
	v_pk_mul_f32 v[78:79], v[82:83], v[78:79]
	v_mov_b32_e32 v82, v71
	v_add_f32_e32 v97, 1.0, v89
	v_rcp_f32_e32 v89, v96
	v_pk_mul_f32 v[70:71], v[82:83], v[84:85]
	v_mov_b32_e32 v82, v72
	v_add_f32_e32 v98, 1.0, v77
	v_rcp_f32_e32 v77, v97
	v_mul_f32_e32 v72, v70, v71
	v_pk_mul_f32 v[70:71], v[82:83], v[80:81]
	v_mov_b32_e32 v82, v73
	v_rcp_f32_e32 v91, v98
	v_mul_f32_e32 v73, v70, v71
	v_pk_mul_f32 v[70:71], v[82:83], v[86:87]
	v_mov_b32_e32 v82, v66
	v_mul_f32_e32 v78, v78, v79
	v_cvt_pk_bf16_f32 v66, v78, v72
	v_mul_f32_e32 v72, v70, v71
	v_pk_mul_f32 v[70:71], v[82:83], v[74:75]
	v_mov_b32_e32 v82, v67
	v_mul_f32_e32 v74, v70, v71
	v_pk_mul_f32 v[70:71], v[82:83], v[88:89]
	v_mov_b32_e32 v82, v68
	v_mul_f32_e32 v68, v70, v71
	v_pk_mul_f32 v[70:71], v[82:83], v[76:77]
	v_mov_b32_e32 v82, v69
	v_mul_f32_e32 v69, v70, v71
	v_pk_mul_f32 v[70:71], v[82:83], v[90:91]
	v_cvt_pk_bf16_f32 v67, v73, v72
	v_cvt_pk_bf16_f32 v68, v74, v68
	v_mov_b32_e32 v74, v61
	v_mul_f32_e32 v70, v70, v71
	v_cvt_pk_bf16_f32 v69, v69, v70
	global_store_dwordx4 v[92:93], v[66:69], off
	s_nop 0
	v_mov_b32_e32 v72, v59
	v_add_u32_e32 v59, 0x80, v142
	v_mad_i64_i32 v[76:77], s[2:3], v59, s60, v[144:145]
	v_mov_b32_e32 v66, v54
	v_mov_b32_e32 v68, v63
	v_mov_b32_e32 v70, v65
	v_lshl_add_u64 v[76:77], v[76:77], 0, v[122:123]
	s_waitcnt vmcnt(7)
	v_mov_b32_e32 v67, v245
	v_fmamk_f32 v61, v67, 0x39800000, v155
	v_rsq_f32_e32 v61, v61
	s_nop 0
	v_mul_f32_e32 v59, 0xbfb8aa3b, v61
	v_mul_f32_e32 v54, v54, v59
	v_mul_f32_e32 v67, v61, v61
	v_mul_f32_e32 v61, v55, v59
	v_mul_f32_e32 v63, v56, v59
	v_exp_f32_e32 v54, v54
	v_mul_f32_e32 v69, v50, v59
	v_exp_f32_e32 v61, v61
	v_exp_f32_e32 v63, v63
	v_mul_f32_e32 v65, v57, v59
	v_exp_f32_e32 v69, v69
	v_mul_f32_e32 v71, v51, v59
	v_exp_f32_e32 v65, v65
	v_mul_f32_e32 v73, v52, v59
	v_mul_f32_e32 v59, v53, v59
	v_exp_f32_e32 v71, v71
	v_add_f32_e32 v54, 1.0, v54
	v_exp_f32_e32 v59, v59
	v_add_f32_e32 v61, 1.0, v61
	v_add_f32_e32 v75, 1.0, v63
	v_rcp_f32_e32 v63, v54
	v_exp_f32_e32 v73, v73
	v_add_f32_e32 v79, 1.0, v69
	v_rcp_f32_e32 v69, v61
	v_add_f32_e32 v78, 1.0, v65
	v_rcp_f32_e32 v65, v75
	v_add_f32_e32 v80, 1.0, v71
	v_rcp_f32_e32 v71, v78
	v_add_f32_e32 v82, 1.0, v59
	v_rcp_f32_e32 v59, v79
	v_pk_mul_f32 v[62:63], v[66:67], v[62:63]
	v_mov_b32_e32 v66, v55
	v_add_f32_e32 v81, 1.0, v73
	v_rcp_f32_e32 v73, v80
	v_pk_mul_f32 v[54:55], v[66:67], v[68:69]
	v_mov_b32_e32 v66, v56
	v_rcp_f32_e32 v61, v81
	v_mul_f32_e32 v56, v54, v55
	v_pk_mul_f32 v[54:55], v[66:67], v[64:65]
	v_mov_b32_e32 v66, v57
	v_rcp_f32_e32 v75, v82
	v_mul_f32_e32 v57, v54, v55
	v_pk_mul_f32 v[54:55], v[66:67], v[70:71]
	v_mov_b32_e32 v66, v50
	v_mul_f32_e32 v62, v62, v63
	v_cvt_pk_bf16_f32 v50, v62, v56
	v_mul_f32_e32 v56, v54, v55
	v_pk_mul_f32 v[54:55], v[66:67], v[58:59]
	v_mov_b32_e32 v66, v51
	v_mul_f32_e32 v58, v54, v55
	v_pk_mul_f32 v[54:55], v[66:67], v[72:73]
	v_mov_b32_e32 v66, v52
	v_mul_f32_e32 v52, v54, v55
	v_pk_mul_f32 v[54:55], v[66:67], v[60:61]
	v_mov_b32_e32 v66, v53
	v_mul_f32_e32 v53, v54, v55
	v_pk_mul_f32 v[54:55], v[66:67], v[74:75]
	v_cvt_pk_bf16_f32 v51, v57, v56
	v_cvt_pk_bf16_f32 v52, v58, v52
	v_mov_b32_e32 v58, v45
	v_mul_f32_e32 v54, v54, v55
	v_cvt_pk_bf16_f32 v53, v53, v54
	global_store_dwordx4 v[76:77], v[50:53], off
	s_nop 0
	v_mov_b32_e32 v56, v43
	v_add_u32_e32 v43, 0x90, v142
	v_mad_i64_i32 v[60:61], s[2:3], v43, s60, v[144:145]
	v_mov_b32_e32 v50, v38
	v_mov_b32_e32 v52, v47
	v_mov_b32_e32 v54, v49
	v_lshl_add_u64 v[60:61], v[60:61], 0, v[122:123]
	s_waitcnt vmcnt(7)
	v_mov_b32_e32 v51, v246
	v_fmamk_f32 v45, v51, 0x39800000, v155
	v_rsq_f32_e32 v45, v45
	s_nop 0
	v_mul_f32_e32 v43, 0xbfb8aa3b, v45
	v_mul_f32_e32 v38, v38, v43
	v_mul_f32_e32 v51, v45, v45
	v_mul_f32_e32 v45, v39, v43
	v_mul_f32_e32 v47, v40, v43
	v_exp_f32_e32 v38, v38
	v_mul_f32_e32 v53, v34, v43
	v_exp_f32_e32 v45, v45
	v_exp_f32_e32 v47, v47
	v_mul_f32_e32 v49, v41, v43
	v_exp_f32_e32 v53, v53
	v_mul_f32_e32 v55, v35, v43
	v_exp_f32_e32 v49, v49
	v_mul_f32_e32 v57, v36, v43
	v_mul_f32_e32 v43, v37, v43
	v_exp_f32_e32 v55, v55
	v_add_f32_e32 v38, 1.0, v38
	v_exp_f32_e32 v43, v43
	v_add_f32_e32 v45, 1.0, v45
	v_add_f32_e32 v59, 1.0, v47
	v_rcp_f32_e32 v47, v38
	v_exp_f32_e32 v57, v57
	v_add_f32_e32 v63, 1.0, v53
	v_rcp_f32_e32 v53, v45
	v_add_f32_e32 v62, 1.0, v49
	v_rcp_f32_e32 v49, v59
	v_add_f32_e32 v64, 1.0, v55
	v_rcp_f32_e32 v55, v62
	v_add_f32_e32 v66, 1.0, v43
	v_rcp_f32_e32 v43, v63
	v_pk_mul_f32 v[46:47], v[50:51], v[46:47]
	v_mov_b32_e32 v50, v39
	v_add_f32_e32 v65, 1.0, v57
	v_rcp_f32_e32 v57, v64
	v_pk_mul_f32 v[38:39], v[50:51], v[52:53]
	v_mov_b32_e32 v50, v40
	v_rcp_f32_e32 v45, v65
	v_mul_f32_e32 v40, v38, v39
	v_pk_mul_f32 v[38:39], v[50:51], v[48:49]
	v_mov_b32_e32 v50, v41
	v_rcp_f32_e32 v59, v66
	v_mul_f32_e32 v41, v38, v39
	v_pk_mul_f32 v[38:39], v[50:51], v[54:55]
	v_mov_b32_e32 v50, v34
	v_mul_f32_e32 v46, v46, v47
	v_cvt_pk_bf16_f32 v34, v46, v40
	v_mul_f32_e32 v40, v38, v39
	v_pk_mul_f32 v[38:39], v[50:51], v[42:43]
	v_mov_b32_e32 v50, v35
	v_mul_f32_e32 v42, v38, v39
	v_pk_mul_f32 v[38:39], v[50:51], v[56:57]
	v_mov_b32_e32 v50, v36
	v_mul_f32_e32 v36, v38, v39
	v_pk_mul_f32 v[38:39], v[50:51], v[44:45]
	v_mov_b32_e32 v50, v37
	v_mul_f32_e32 v37, v38, v39
	v_pk_mul_f32 v[38:39], v[50:51], v[58:59]
	v_cvt_pk_bf16_f32 v35, v41, v40
	v_cvt_pk_bf16_f32 v36, v42, v36
	v_mov_b32_e32 v42, v29
	v_mul_f32_e32 v38, v38, v39
	v_cvt_pk_bf16_f32 v37, v37, v38
	global_store_dwordx4 v[60:61], v[34:37], off
	s_nop 0
	v_mov_b32_e32 v40, v27
	v_add_u32_e32 v27, 0xa0, v142
	v_mad_i64_i32 v[44:45], s[2:3], v27, s60, v[144:145]
	v_mov_b32_e32 v34, v22
	v_mov_b32_e32 v36, v31
	v_mov_b32_e32 v38, v33
	v_lshl_add_u64 v[44:45], v[44:45], 0, v[122:123]
	s_waitcnt vmcnt(7)
	v_mov_b32_e32 v35, v247
	v_fmamk_f32 v29, v35, 0x39800000, v155
	v_rsq_f32_e32 v29, v29
	s_nop 0
	v_mul_f32_e32 v27, 0xbfb8aa3b, v29
	v_mul_f32_e32 v22, v22, v27
	v_mul_f32_e32 v35, v29, v29
	v_mul_f32_e32 v29, v23, v27
	v_mul_f32_e32 v31, v24, v27
	v_exp_f32_e32 v22, v22
	v_mul_f32_e32 v37, v18, v27
	v_exp_f32_e32 v29, v29
	v_exp_f32_e32 v31, v31
	v_mul_f32_e32 v33, v25, v27
	v_exp_f32_e32 v37, v37
	v_mul_f32_e32 v39, v19, v27
	v_exp_f32_e32 v33, v33
	v_mul_f32_e32 v41, v20, v27
	v_mul_f32_e32 v27, v21, v27
	v_exp_f32_e32 v39, v39
	v_add_f32_e32 v22, 1.0, v22
	v_exp_f32_e32 v27, v27
	v_add_f32_e32 v29, 1.0, v29
	v_add_f32_e32 v43, 1.0, v31
	v_rcp_f32_e32 v31, v22
	v_exp_f32_e32 v41, v41
	v_add_f32_e32 v47, 1.0, v37
	v_rcp_f32_e32 v37, v29
	v_add_f32_e32 v46, 1.0, v33
	v_rcp_f32_e32 v33, v43
	v_add_f32_e32 v48, 1.0, v39
	v_rcp_f32_e32 v39, v46
	v_add_f32_e32 v50, 1.0, v27
	v_rcp_f32_e32 v27, v47
	v_pk_mul_f32 v[30:31], v[34:35], v[30:31]
	v_mov_b32_e32 v34, v23
	v_add_f32_e32 v49, 1.0, v41
	v_rcp_f32_e32 v41, v48
	v_pk_mul_f32 v[22:23], v[34:35], v[36:37]
	v_mov_b32_e32 v34, v24
	v_rcp_f32_e32 v29, v49
	v_mul_f32_e32 v24, v22, v23
	v_pk_mul_f32 v[22:23], v[34:35], v[32:33]
	v_mov_b32_e32 v34, v25
	v_rcp_f32_e32 v43, v50
	v_mul_f32_e32 v25, v22, v23
	v_pk_mul_f32 v[22:23], v[34:35], v[38:39]
	v_mov_b32_e32 v34, v18
	v_mul_f32_e32 v30, v30, v31
	v_cvt_pk_bf16_f32 v18, v30, v24
	v_mul_f32_e32 v24, v22, v23
	v_pk_mul_f32 v[22:23], v[34:35], v[26:27]
	v_mov_b32_e32 v34, v19
	v_mul_f32_e32 v26, v22, v23
	v_pk_mul_f32 v[22:23], v[34:35], v[40:41]
	v_mov_b32_e32 v34, v20
	v_mul_f32_e32 v20, v22, v23
	v_pk_mul_f32 v[22:23], v[34:35], v[28:29]
	v_mov_b32_e32 v34, v21
	v_mul_f32_e32 v21, v22, v23
	v_pk_mul_f32 v[22:23], v[34:35], v[42:43]
	v_cvt_pk_bf16_f32 v19, v25, v24
	v_cvt_pk_bf16_f32 v20, v26, v20
	v_mov_b32_e32 v26, v13
	v_mul_f32_e32 v22, v22, v23
	v_cvt_pk_bf16_f32 v21, v21, v22
	global_store_dwordx4 v[44:45], v[18:21], off
	s_nop 0
	v_mov_b32_e32 v24, v11
	v_add_u32_e32 v11, 0xb0, v142
	v_mad_i64_i32 v[28:29], s[2:3], v11, s60, v[144:145]
	v_mov_b32_e32 v18, v6
	v_mov_b32_e32 v20, v15
	v_mov_b32_e32 v22, v17
	v_lshl_add_u64 v[28:29], v[28:29], 0, v[122:123]
	s_mov_b64 s[2:3], -1
	s_waitcnt vmcnt(7)
	v_mov_b32_e32 v19, v248
	v_fmamk_f32 v13, v19, 0x39800000, v155
	v_rsq_f32_e32 v13, v13
	s_nop 0
	v_mul_f32_e32 v11, 0xbfb8aa3b, v13
	v_mul_f32_e32 v6, v6, v11
	v_mul_f32_e32 v19, v13, v13
	v_mul_f32_e32 v13, v7, v11
	v_mul_f32_e32 v15, v8, v11
	v_exp_f32_e32 v6, v6
	v_mul_f32_e32 v21, v2, v11
	v_exp_f32_e32 v13, v13
	v_exp_f32_e32 v15, v15
	v_mul_f32_e32 v17, v9, v11
	v_exp_f32_e32 v21, v21
	v_mul_f32_e32 v23, v3, v11
	v_exp_f32_e32 v17, v17
	v_mul_f32_e32 v25, v4, v11
	v_mul_f32_e32 v11, v5, v11
	v_exp_f32_e32 v23, v23
	v_add_f32_e32 v6, 1.0, v6
	v_exp_f32_e32 v11, v11
	v_add_f32_e32 v13, 1.0, v13
	v_add_f32_e32 v27, 1.0, v15
	v_rcp_f32_e32 v15, v6
	v_exp_f32_e32 v25, v25
	v_add_f32_e32 v31, 1.0, v21
	v_rcp_f32_e32 v21, v13
	v_add_f32_e32 v30, 1.0, v17
	v_rcp_f32_e32 v17, v27
	v_add_f32_e32 v32, 1.0, v23
	v_rcp_f32_e32 v23, v30
	v_add_f32_e32 v34, 1.0, v11
	v_rcp_f32_e32 v11, v31
	v_pk_mul_f32 v[14:15], v[18:19], v[14:15]
	v_mov_b32_e32 v18, v7
	v_add_f32_e32 v33, 1.0, v25
	v_rcp_f32_e32 v25, v32
	v_pk_mul_f32 v[6:7], v[18:19], v[20:21]
	v_mov_b32_e32 v18, v8
	v_rcp_f32_e32 v13, v33
	v_mul_f32_e32 v8, v6, v7
	v_pk_mul_f32 v[6:7], v[18:19], v[16:17]
	v_mov_b32_e32 v18, v9
	v_rcp_f32_e32 v27, v34
	v_mul_f32_e32 v9, v6, v7
	v_pk_mul_f32 v[6:7], v[18:19], v[22:23]
	v_mov_b32_e32 v18, v2
	v_mul_f32_e32 v14, v14, v15
	v_cvt_pk_bf16_f32 v2, v14, v8
	v_mul_f32_e32 v8, v6, v7
	v_pk_mul_f32 v[6:7], v[18:19], v[10:11]
	v_mov_b32_e32 v18, v3
	v_mul_f32_e32 v10, v6, v7
	v_pk_mul_f32 v[6:7], v[18:19], v[24:25]
	v_mov_b32_e32 v18, v4
	v_mul_f32_e32 v4, v6, v7
	v_pk_mul_f32 v[6:7], v[18:19], v[12:13]
	v_mov_b32_e32 v18, v5
	v_mul_f32_e32 v5, v6, v7
	v_pk_mul_f32 v[6:7], v[18:19], v[26:27]
	v_cvt_pk_bf16_f32 v3, v9, v8
	v_cvt_pk_bf16_f32 v4, v10, v4
	s_nop 0
	v_mul_f32_e32 v6, v6, v7
	v_cvt_pk_bf16_f32 v5, v5, v6
	global_store_dwordx4 v[28:29], v[2:5], off
	s_cbranch_vccnz .LBB0_401
	s_andn2_b64 vcc, exec, s[0:1]
	s_cbranch_vccnz .LBB0_400
	s_barrier
	s_branch .LBB0_400

.LBB0_1336:
	v_lshl_add_u32 v142, s22, 8, v153
	v_ashrrev_i32_e32 v143, 31, v142
	v_lshl_add_u64 v[146:147], v[142:143], 2, s[4:5]
	global_load_dword v241, v[146:147], off
	global_load_dword v242, v[146:147], off offset:64
	global_load_dword v243, v[146:147], off offset:128
	global_load_dword v244, v[146:147], off offset:192
	global_load_dword v245, v[146:147], off offset:512
	global_load_dword v246, v[146:147], off offset:576
	global_load_dword v247, v[146:147], off offset:640
	global_load_dword v248, v[146:147], off offset:704
	v_mov_b32_e32 v176, v125
	v_mov_b32_e32 v168, v127
	v_mov_b32_e32 v166, v118
	v_mov_b32_e32 v170, v129
	v_lshl_or_b32 v164, s18, 7, v158
	v_mov_b64_e32 v[144:145], s[6:7]
	v_ashrrev_i32_e32 v165, 31, v164
	v_or_b32_e32 v180, 16, v142
	v_mov_b32_e32 v172, v122
	v_mov_b32_e32 v174, v123
	v_mad_i64_i32 v[178:179], s[2:3], v142, s57, v[144:145]
	v_lshlrev_b64 v[122:123], 1, v[164:165]
	v_ashrrev_i32_e32 v181, 31, v180
	v_lshl_add_u64 v[164:165], v[178:179], 0, v[122:123]
	v_lshl_add_u64 v[178:179], v[180:181], 2, s[4:5]
	s_andn2_b64 vcc, exec, s[26:27]
	s_waitcnt vmcnt(7)
	v_mov_b32_e32 v143, v241
	v_fmamk_f32 v125, v143, 0x39800000, v162
	v_rsq_f32_e32 v125, v125
	s_nop 0
	v_mul_f32_e32 v127, 0xbfb8aa3b, v125
	v_mul_f32_e32 v118, v118, v127
	v_mul_f32_e32 v167, v125, v125
	v_mul_f32_e32 v125, v119, v127
	v_mul_f32_e32 v129, v120, v127
	v_mul_f32_e32 v143, v121, v127
	v_mul_f32_e32 v163, v114, v127
	v_mul_f32_e32 v169, v115, v127
	v_mul_f32_e32 v171, v116, v127
	v_mul_f32_e32 v127, v117, v127
	v_exp_f32_e32 v118, v118
	v_exp_f32_e32 v125, v125
	v_exp_f32_e32 v127, v127
	v_exp_f32_e32 v129, v129
	v_exp_f32_e32 v169, v169
	v_exp_f32_e32 v143, v143
	v_exp_f32_e32 v163, v163
	v_exp_f32_e32 v171, v171
	v_add_f32_e32 v118, 1.0, v118
	v_add_f32_e32 v125, 1.0, v125
	v_add_f32_e32 v181, 1.0, v127
	v_rcp_f32_e32 v127, v118
	v_add_f32_e32 v129, 1.0, v129
	v_add_f32_e32 v175, 1.0, v169
	v_rcp_f32_e32 v169, v125
	v_add_f32_e32 v143, 1.0, v143
	v_rcp_f32_e32 v129, v129
	v_add_f32_e32 v163, 1.0, v163
	v_add_f32_e32 v177, 1.0, v171
	v_rcp_f32_e32 v171, v143
	v_rcp_f32_e32 v173, v163
	v_pk_mul_f32 v[126:127], v[166:167], v[126:127]
	v_mov_b32_e32 v166, v119
	v_rcp_f32_e32 v175, v175
	v_pk_mul_f32 v[118:119], v[166:167], v[168:169]
	v_mov_b32_e32 v166, v120
	v_rcp_f32_e32 v125, v177
	v_mul_f32_e32 v120, v118, v119
	v_pk_mul_f32 v[118:119], v[166:167], v[128:129]
	v_mov_b32_e32 v166, v121
	v_rcp_f32_e32 v177, v181
	v_mul_f32_e32 v121, v118, v119
	v_pk_mul_f32 v[118:119], v[166:167], v[170:171]
	v_mov_b32_e32 v166, v114
	v_mul_f32_e32 v126, v126, v127
	v_cvt_pk_bf16_f32 v114, v126, v120
	v_mul_f32_e32 v120, v118, v119
	v_pk_mul_f32 v[118:119], v[166:167], v[172:173]
	v_mov_b32_e32 v166, v115
	v_mul_f32_e32 v126, v118, v119
	v_pk_mul_f32 v[118:119], v[166:167], v[174:175]
	v_mov_b32_e32 v166, v116
	v_mul_f32_e32 v116, v118, v119
	v_pk_mul_f32 v[118:119], v[166:167], v[124:125]
	v_mov_b32_e32 v166, v117
	v_mul_f32_e32 v117, v118, v119
	v_pk_mul_f32 v[118:119], v[166:167], v[176:177]
	v_cvt_pk_bf16_f32 v115, v121, v120
	v_cvt_pk_bf16_f32 v116, v126, v116
	v_mov_b32_e32 v120, v107
	v_mul_f32_e32 v118, v118, v119
	v_cvt_pk_bf16_f32 v117, v117, v118
	global_store_dwordx4 v[164:165], v[114:117], off
	s_nop 0
	v_mov_b32_e32 v124, v109
	v_mov_b32_e32 v114, v102
	v_mov_b32_e32 v116, v111
	v_mov_b32_e32 v118, v113
	v_or_b32_e32 v126, 32, v142
	v_ashrrev_i32_e32 v127, 31, v126
	v_lshl_add_u64 v[164:165], v[126:127], 2, s[4:5]
	v_mad_i64_i32 v[128:129], s[2:3], v180, s57, v[144:145]
	v_lshl_add_u64 v[128:129], v[128:129], 0, v[122:123]
	s_waitcnt vmcnt(7)
	v_mov_b32_e32 v115, v242
	v_fmamk_f32 v107, v115, 0x39800000, v162
	v_rsq_f32_e32 v107, v107
	s_nop 0
	v_mul_f32_e32 v109, 0xbfb8aa3b, v107
	v_mul_f32_e32 v102, v102, v109
	v_mul_f32_e32 v115, v107, v107
	v_mul_f32_e32 v107, v103, v109
	v_mul_f32_e32 v111, v104, v109
	v_exp_f32_e32 v102, v102
	v_mul_f32_e32 v117, v98, v109
	v_exp_f32_e32 v107, v107
	v_exp_f32_e32 v111, v111
	v_mul_f32_e32 v113, v105, v109
	v_exp_f32_e32 v117, v117
	v_mul_f32_e32 v119, v99, v109
	v_exp_f32_e32 v113, v113
	v_exp_f32_e32 v119, v119
	v_add_f32_e32 v102, 1.0, v102
	v_mul_f32_e32 v121, v100, v109
	v_add_f32_e32 v107, 1.0, v107
	v_add_f32_e32 v125, 1.0, v111
	v_rcp_f32_e32 v111, v102
	v_mul_f32_e32 v109, v101, v109
	v_exp_f32_e32 v121, v121
	v_add_f32_e32 v143, 1.0, v117
	v_rcp_f32_e32 v117, v107
	v_exp_f32_e32 v109, v109
	v_add_f32_e32 v127, 1.0, v113
	v_rcp_f32_e32 v113, v125
	v_add_f32_e32 v163, 1.0, v119
	v_rcp_f32_e32 v119, v127
	v_rcp_f32_e32 v107, v143
	v_pk_mul_f32 v[110:111], v[114:115], v[110:111]
	v_mov_b32_e32 v114, v103
	v_add_f32_e32 v166, 1.0, v121
	v_rcp_f32_e32 v121, v163
	v_pk_mul_f32 v[102:103], v[114:115], v[116:117]
	v_mov_b32_e32 v114, v104
	v_add_f32_e32 v167, 1.0, v109
	v_rcp_f32_e32 v109, v166
	v_mul_f32_e32 v104, v102, v103
	v_pk_mul_f32 v[102:103], v[114:115], v[112:113]
	v_mov_b32_e32 v114, v105
	v_rcp_f32_e32 v125, v167
	v_mul_f32_e32 v105, v102, v103
	v_pk_mul_f32 v[102:103], v[114:115], v[118:119]
	v_mov_b32_e32 v114, v98
	v_mul_f32_e32 v110, v110, v111
	v_cvt_pk_bf16_f32 v98, v110, v104
	v_mul_f32_e32 v104, v102, v103
	v_pk_mul_f32 v[102:103], v[114:115], v[106:107]
	v_mov_b32_e32 v114, v99
	v_mul_f32_e32 v106, v102, v103
	v_pk_mul_f32 v[102:103], v[114:115], v[120:121]
	v_mov_b32_e32 v114, v100
	v_mul_f32_e32 v100, v102, v103
	v_pk_mul_f32 v[102:103], v[114:115], v[108:109]
	v_mov_b32_e32 v114, v101
	v_mul_f32_e32 v101, v102, v103
	v_pk_mul_f32 v[102:103], v[114:115], v[124:125]
	v_cvt_pk_bf16_f32 v99, v105, v104
	v_cvt_pk_bf16_f32 v100, v106, v100
	v_mov_b32_e32 v104, v91
	v_mul_f32_e32 v102, v102, v103
	v_cvt_pk_bf16_f32 v101, v101, v102
	global_store_dwordx4 v[128:129], v[98:101], off
	s_nop 0
	v_mov_b32_e32 v106, v93
	v_mov_b32_e32 v98, v86
	v_mov_b32_e32 v100, v95
	v_mov_b32_e32 v102, v97
	v_or_b32_e32 v108, 48, v142
	v_ashrrev_i32_e32 v109, 31, v108
	v_lshl_add_u64 v[112:113], v[108:109], 2, s[4:5]
	v_mad_i64_i32 v[110:111], s[2:3], v126, s57, v[144:145]
	v_lshl_add_u64 v[110:111], v[110:111], 0, v[122:123]
	s_waitcnt vmcnt(7)
	v_mov_b32_e32 v99, v243
	v_fmamk_f32 v91, v99, 0x39800000, v162
	v_rsq_f32_e32 v91, v91
	s_nop 0
	v_mul_f32_e32 v93, 0xbfb8aa3b, v91
	v_mul_f32_e32 v86, v86, v93
	v_mul_f32_e32 v99, v91, v91
	v_mul_f32_e32 v91, v87, v93
	v_mul_f32_e32 v95, v88, v93
	v_exp_f32_e32 v86, v86
	v_mul_f32_e32 v101, v82, v93
	v_exp_f32_e32 v91, v91
	v_exp_f32_e32 v95, v95
	v_mul_f32_e32 v97, v89, v93
	v_exp_f32_e32 v101, v101
	v_mul_f32_e32 v103, v83, v93
	v_exp_f32_e32 v97, v97
	v_exp_f32_e32 v103, v103
	v_add_f32_e32 v86, 1.0, v86
	v_mul_f32_e32 v105, v84, v93
	v_add_f32_e32 v91, 1.0, v91
	v_add_f32_e32 v107, 1.0, v95
	v_rcp_f32_e32 v95, v86
	v_mul_f32_e32 v93, v85, v93
	v_exp_f32_e32 v105, v105
	v_add_f32_e32 v114, 1.0, v101
	v_rcp_f32_e32 v101, v91
	v_exp_f32_e32 v93, v93
	v_add_f32_e32 v109, 1.0, v97
	v_rcp_f32_e32 v97, v107
	v_add_f32_e32 v115, 1.0, v103
	v_rcp_f32_e32 v103, v109
	v_rcp_f32_e32 v91, v114
	v_pk_mul_f32 v[94:95], v[98:99], v[94:95]
	v_mov_b32_e32 v98, v87
	v_add_f32_e32 v116, 1.0, v105
	v_rcp_f32_e32 v105, v115
	v_pk_mul_f32 v[86:87], v[98:99], v[100:101]
	v_mov_b32_e32 v98, v88
	v_add_f32_e32 v117, 1.0, v93
	v_rcp_f32_e32 v93, v116
	v_mul_f32_e32 v88, v86, v87
	v_pk_mul_f32 v[86:87], v[98:99], v[96:97]
	v_mov_b32_e32 v98, v89
	v_rcp_f32_e32 v107, v117
	v_mul_f32_e32 v89, v86, v87
	v_pk_mul_f32 v[86:87], v[98:99], v[102:103]
	v_mov_b32_e32 v98, v82
	v_mul_f32_e32 v94, v94, v95
	v_cvt_pk_bf16_f32 v82, v94, v88
	v_mul_f32_e32 v88, v86, v87
	v_pk_mul_f32 v[86:87], v[98:99], v[90:91]
	v_mov_b32_e32 v98, v83
	v_mul_f32_e32 v90, v86, v87
	v_pk_mul_f32 v[86:87], v[98:99], v[104:105]
	v_mov_b32_e32 v98, v84
	v_mul_f32_e32 v84, v86, v87
	v_pk_mul_f32 v[86:87], v[98:99], v[92:93]
	v_mov_b32_e32 v98, v85
	v_mul_f32_e32 v85, v86, v87
	v_pk_mul_f32 v[86:87], v[98:99], v[106:107]
	v_cvt_pk_bf16_f32 v83, v89, v88
	v_cvt_pk_bf16_f32 v84, v90, v84
	v_mov_b32_e32 v88, v75
	v_mul_f32_e32 v86, v86, v87
	v_cvt_pk_bf16_f32 v85, v85, v86
	global_store_dwordx4 v[110:111], v[82:85], off
	s_nop 0
	v_mov_b32_e32 v90, v77
	v_mov_b32_e32 v82, v70
	v_mov_b32_e32 v84, v79
	v_mov_b32_e32 v86, v81
	v_mad_i64_i32 v[92:93], s[2:3], v108, s57, v[144:145]
	v_lshl_add_u64 v[92:93], v[92:93], 0, v[122:123]
	s_waitcnt vmcnt(7)
	v_mov_b32_e32 v83, v244
	v_fmamk_f32 v75, v83, 0x39800000, v162
	v_rsq_f32_e32 v75, v75
	s_nop 0
	v_mul_f32_e32 v77, 0xbfb8aa3b, v75
	v_mul_f32_e32 v70, v70, v77
	v_mul_f32_e32 v83, v75, v75
	v_mul_f32_e32 v75, v71, v77
	v_mul_f32_e32 v79, v72, v77
	v_exp_f32_e32 v70, v70
	v_mul_f32_e32 v85, v66, v77
	v_exp_f32_e32 v75, v75
	v_exp_f32_e32 v79, v79
	v_mul_f32_e32 v81, v73, v77
	v_exp_f32_e32 v85, v85
	v_mul_f32_e32 v87, v67, v77
	v_exp_f32_e32 v81, v81
	v_exp_f32_e32 v87, v87
	v_add_f32_e32 v70, 1.0, v70
	v_mul_f32_e32 v89, v68, v77
	v_add_f32_e32 v75, 1.0, v75
	v_add_f32_e32 v91, 1.0, v79
	v_rcp_f32_e32 v79, v70
	v_mul_f32_e32 v77, v69, v77
	v_exp_f32_e32 v89, v89
	v_add_f32_e32 v95, 1.0, v85
	v_rcp_f32_e32 v85, v75
	v_exp_f32_e32 v77, v77
	v_add_f32_e32 v94, 1.0, v81
	v_rcp_f32_e32 v81, v91
	v_add_f32_e32 v96, 1.0, v87
	v_rcp_f32_e32 v87, v94
	v_rcp_f32_e32 v75, v95
	v_pk_mul_f32 v[78:79], v[82:83], v[78:79]
	v_mov_b32_e32 v82, v71
	v_add_f32_e32 v97, 1.0, v89
	v_rcp_f32_e32 v89, v96
	v_pk_mul_f32 v[70:71], v[82:83], v[84:85]
	v_mov_b32_e32 v82, v72
	v_add_f32_e32 v98, 1.0, v77
	v_rcp_f32_e32 v77, v97
	v_mul_f32_e32 v72, v70, v71
	v_pk_mul_f32 v[70:71], v[82:83], v[80:81]
	v_mov_b32_e32 v82, v73
	v_rcp_f32_e32 v91, v98
	v_mul_f32_e32 v73, v70, v71
	v_pk_mul_f32 v[70:71], v[82:83], v[86:87]
	v_mov_b32_e32 v82, v66
	v_mul_f32_e32 v78, v78, v79
	v_cvt_pk_bf16_f32 v66, v78, v72
	v_mul_f32_e32 v72, v70, v71
	v_pk_mul_f32 v[70:71], v[82:83], v[74:75]
	v_mov_b32_e32 v82, v67
	v_mul_f32_e32 v74, v70, v71
	v_pk_mul_f32 v[70:71], v[82:83], v[88:89]
	v_mov_b32_e32 v82, v68
	v_mul_f32_e32 v68, v70, v71
	v_pk_mul_f32 v[70:71], v[82:83], v[76:77]
	v_mov_b32_e32 v82, v69
	v_mul_f32_e32 v69, v70, v71
	v_pk_mul_f32 v[70:71], v[82:83], v[90:91]
	v_cvt_pk_bf16_f32 v67, v73, v72
	v_cvt_pk_bf16_f32 v68, v74, v68
	v_mov_b32_e32 v74, v61
	v_mul_f32_e32 v70, v70, v71
	v_cvt_pk_bf16_f32 v69, v69, v70
	global_store_dwordx4 v[92:93], v[66:69], off
	s_nop 0
	v_mov_b32_e32 v72, v59
	v_add_u32_e32 v59, 0x80, v142
	v_mad_i64_i32 v[76:77], s[2:3], v59, s57, v[144:145]
	v_mov_b32_e32 v66, v54
	v_mov_b32_e32 v68, v63
	v_mov_b32_e32 v70, v65
	v_lshl_add_u64 v[76:77], v[76:77], 0, v[122:123]
	s_waitcnt vmcnt(7)
	v_mov_b32_e32 v67, v245
	v_fmamk_f32 v61, v67, 0x39800000, v162
	v_rsq_f32_e32 v61, v61
	s_nop 0
	v_mul_f32_e32 v59, 0xbfb8aa3b, v61
	v_mul_f32_e32 v54, v54, v59
	v_mul_f32_e32 v67, v61, v61
	v_mul_f32_e32 v61, v55, v59
	v_mul_f32_e32 v63, v56, v59
	v_exp_f32_e32 v54, v54
	v_mul_f32_e32 v69, v50, v59
	v_exp_f32_e32 v61, v61
	v_exp_f32_e32 v63, v63
	v_mul_f32_e32 v65, v57, v59
	v_exp_f32_e32 v69, v69
	v_mul_f32_e32 v71, v51, v59
	v_exp_f32_e32 v65, v65
	v_mul_f32_e32 v73, v52, v59
	v_mul_f32_e32 v59, v53, v59
	v_exp_f32_e32 v71, v71
	v_add_f32_e32 v54, 1.0, v54
	v_exp_f32_e32 v59, v59
	v_add_f32_e32 v61, 1.0, v61
	v_add_f32_e32 v75, 1.0, v63
	v_rcp_f32_e32 v63, v54
	v_exp_f32_e32 v73, v73
	v_add_f32_e32 v79, 1.0, v69
	v_rcp_f32_e32 v69, v61
	v_add_f32_e32 v78, 1.0, v65
	v_rcp_f32_e32 v65, v75
	v_add_f32_e32 v80, 1.0, v71
	v_rcp_f32_e32 v71, v78
	v_add_f32_e32 v82, 1.0, v59
	v_rcp_f32_e32 v59, v79
	v_pk_mul_f32 v[62:63], v[66:67], v[62:63]
	v_mov_b32_e32 v66, v55
	v_add_f32_e32 v81, 1.0, v73
	v_rcp_f32_e32 v73, v80
	v_pk_mul_f32 v[54:55], v[66:67], v[68:69]
	v_mov_b32_e32 v66, v56
	v_rcp_f32_e32 v61, v81
	v_mul_f32_e32 v56, v54, v55
	v_pk_mul_f32 v[54:55], v[66:67], v[64:65]
	v_mov_b32_e32 v66, v57
	v_rcp_f32_e32 v75, v82
	v_mul_f32_e32 v57, v54, v55
	v_pk_mul_f32 v[54:55], v[66:67], v[70:71]
	v_mov_b32_e32 v66, v50
	v_mul_f32_e32 v62, v62, v63
	v_cvt_pk_bf16_f32 v50, v62, v56
	v_mul_f32_e32 v56, v54, v55
	v_pk_mul_f32 v[54:55], v[66:67], v[58:59]
	v_mov_b32_e32 v66, v51
	v_mul_f32_e32 v58, v54, v55
	v_pk_mul_f32 v[54:55], v[66:67], v[72:73]
	v_mov_b32_e32 v66, v52
	v_mul_f32_e32 v52, v54, v55
	v_pk_mul_f32 v[54:55], v[66:67], v[60:61]
	v_mov_b32_e32 v66, v53
	v_mul_f32_e32 v53, v54, v55
	v_pk_mul_f32 v[54:55], v[66:67], v[74:75]
	v_cvt_pk_bf16_f32 v51, v57, v56
	v_cvt_pk_bf16_f32 v52, v58, v52
	v_mov_b32_e32 v58, v45
	v_mul_f32_e32 v54, v54, v55
	v_cvt_pk_bf16_f32 v53, v53, v54
	global_store_dwordx4 v[76:77], v[50:53], off
	s_nop 0
	v_mov_b32_e32 v56, v43
	v_add_u32_e32 v43, 0x90, v142
	v_mad_i64_i32 v[60:61], s[2:3], v43, s57, v[144:145]
	v_mov_b32_e32 v50, v38
	v_mov_b32_e32 v52, v47
	v_mov_b32_e32 v54, v49
	v_lshl_add_u64 v[60:61], v[60:61], 0, v[122:123]
	s_waitcnt vmcnt(7)
	v_mov_b32_e32 v51, v246
	v_fmamk_f32 v45, v51, 0x39800000, v162
	v_rsq_f32_e32 v45, v45
	s_nop 0
	v_mul_f32_e32 v43, 0xbfb8aa3b, v45
	v_mul_f32_e32 v38, v38, v43
	v_mul_f32_e32 v51, v45, v45
	v_mul_f32_e32 v45, v39, v43
	v_mul_f32_e32 v47, v40, v43
	v_exp_f32_e32 v38, v38
	v_mul_f32_e32 v53, v34, v43
	v_exp_f32_e32 v45, v45
	v_exp_f32_e32 v47, v47
	v_mul_f32_e32 v49, v41, v43
	v_exp_f32_e32 v53, v53
	v_mul_f32_e32 v55, v35, v43
	v_exp_f32_e32 v49, v49
	v_mul_f32_e32 v57, v36, v43
	v_mul_f32_e32 v43, v37, v43
	v_exp_f32_e32 v55, v55
	v_add_f32_e32 v38, 1.0, v38
	v_exp_f32_e32 v43, v43
	v_add_f32_e32 v45, 1.0, v45
	v_add_f32_e32 v59, 1.0, v47
	v_rcp_f32_e32 v47, v38
	v_exp_f32_e32 v57, v57
	v_add_f32_e32 v63, 1.0, v53
	v_rcp_f32_e32 v53, v45
	v_add_f32_e32 v62, 1.0, v49
	v_rcp_f32_e32 v49, v59
	v_add_f32_e32 v64, 1.0, v55
	v_rcp_f32_e32 v55, v62
	v_add_f32_e32 v66, 1.0, v43
	v_rcp_f32_e32 v43, v63
	v_pk_mul_f32 v[46:47], v[50:51], v[46:47]
	v_mov_b32_e32 v50, v39
	v_add_f32_e32 v65, 1.0, v57
	v_rcp_f32_e32 v57, v64
	v_pk_mul_f32 v[38:39], v[50:51], v[52:53]
	v_mov_b32_e32 v50, v40
	v_rcp_f32_e32 v45, v65
	v_mul_f32_e32 v40, v38, v39
	v_pk_mul_f32 v[38:39], v[50:51], v[48:49]
	v_mov_b32_e32 v50, v41
	v_rcp_f32_e32 v59, v66
	v_mul_f32_e32 v41, v38, v39
	v_pk_mul_f32 v[38:39], v[50:51], v[54:55]
	v_mov_b32_e32 v50, v34
	v_mul_f32_e32 v46, v46, v47
	v_cvt_pk_bf16_f32 v34, v46, v40
	v_mul_f32_e32 v40, v38, v39
	v_pk_mul_f32 v[38:39], v[50:51], v[42:43]
	v_mov_b32_e32 v50, v35
	v_mul_f32_e32 v42, v38, v39
	v_pk_mul_f32 v[38:39], v[50:51], v[56:57]
	v_mov_b32_e32 v50, v36
	v_mul_f32_e32 v36, v38, v39
	v_pk_mul_f32 v[38:39], v[50:51], v[44:45]
	v_mov_b32_e32 v50, v37
	v_mul_f32_e32 v37, v38, v39
	v_pk_mul_f32 v[38:39], v[50:51], v[58:59]
	v_cvt_pk_bf16_f32 v35, v41, v40
	v_cvt_pk_bf16_f32 v36, v42, v36
	v_mov_b32_e32 v42, v29
	v_mul_f32_e32 v38, v38, v39
	v_cvt_pk_bf16_f32 v37, v37, v38
	global_store_dwordx4 v[60:61], v[34:37], off
	s_nop 0
	v_mov_b32_e32 v40, v27
	v_add_u32_e32 v27, 0xa0, v142
	v_mad_i64_i32 v[44:45], s[2:3], v27, s57, v[144:145]
	v_mov_b32_e32 v34, v22
	v_mov_b32_e32 v36, v31
	v_mov_b32_e32 v38, v33
	v_lshl_add_u64 v[44:45], v[44:45], 0, v[122:123]
	s_waitcnt vmcnt(7)
	v_mov_b32_e32 v35, v247
	v_fmamk_f32 v29, v35, 0x39800000, v162
	v_rsq_f32_e32 v29, v29
	s_nop 0
	v_mul_f32_e32 v27, 0xbfb8aa3b, v29
	v_mul_f32_e32 v22, v22, v27
	v_mul_f32_e32 v35, v29, v29
	v_mul_f32_e32 v29, v23, v27
	v_mul_f32_e32 v31, v24, v27
	v_exp_f32_e32 v22, v22
	v_mul_f32_e32 v37, v18, v27
	v_exp_f32_e32 v29, v29
	v_exp_f32_e32 v31, v31
	v_mul_f32_e32 v33, v25, v27
	v_exp_f32_e32 v37, v37
	v_mul_f32_e32 v39, v19, v27
	v_exp_f32_e32 v33, v33
	v_mul_f32_e32 v41, v20, v27
	v_mul_f32_e32 v27, v21, v27
	v_exp_f32_e32 v39, v39
	v_add_f32_e32 v22, 1.0, v22
	v_exp_f32_e32 v27, v27
	v_add_f32_e32 v29, 1.0, v29
	v_add_f32_e32 v43, 1.0, v31
	v_rcp_f32_e32 v31, v22
	v_exp_f32_e32 v41, v41
	v_add_f32_e32 v47, 1.0, v37
	v_rcp_f32_e32 v37, v29
	v_add_f32_e32 v46, 1.0, v33
	v_rcp_f32_e32 v33, v43
	v_add_f32_e32 v48, 1.0, v39
	v_rcp_f32_e32 v39, v46
	v_add_f32_e32 v50, 1.0, v27
	v_rcp_f32_e32 v27, v47
	v_pk_mul_f32 v[30:31], v[34:35], v[30:31]
	v_mov_b32_e32 v34, v23
	v_add_f32_e32 v49, 1.0, v41
	v_rcp_f32_e32 v41, v48
	v_pk_mul_f32 v[22:23], v[34:35], v[36:37]
	v_mov_b32_e32 v34, v24
	v_rcp_f32_e32 v29, v49
	v_mul_f32_e32 v24, v22, v23
	v_pk_mul_f32 v[22:23], v[34:35], v[32:33]
	v_mov_b32_e32 v34, v25
	v_rcp_f32_e32 v43, v50
	v_mul_f32_e32 v25, v22, v23
	v_pk_mul_f32 v[22:23], v[34:35], v[38:39]
	v_mov_b32_e32 v34, v18
	v_mul_f32_e32 v30, v30, v31
	v_cvt_pk_bf16_f32 v18, v30, v24
	v_mul_f32_e32 v24, v22, v23
	v_pk_mul_f32 v[22:23], v[34:35], v[26:27]
	v_mov_b32_e32 v34, v19
	v_mul_f32_e32 v26, v22, v23
	v_pk_mul_f32 v[22:23], v[34:35], v[40:41]
	v_mov_b32_e32 v34, v20
	v_mul_f32_e32 v20, v22, v23
	v_pk_mul_f32 v[22:23], v[34:35], v[28:29]
	v_mov_b32_e32 v34, v21
	v_mul_f32_e32 v21, v22, v23
	v_pk_mul_f32 v[22:23], v[34:35], v[42:43]
	v_cvt_pk_bf16_f32 v19, v25, v24
	v_cvt_pk_bf16_f32 v20, v26, v20
	v_mov_b32_e32 v26, v13
	v_mul_f32_e32 v22, v22, v23
	v_cvt_pk_bf16_f32 v21, v21, v22
	global_store_dwordx4 v[44:45], v[18:21], off
	s_nop 0
	v_mov_b32_e32 v24, v11
	v_add_u32_e32 v11, 0xb0, v142
	v_mad_i64_i32 v[28:29], s[2:3], v11, s57, v[144:145]
	v_mov_b32_e32 v18, v6
	v_mov_b32_e32 v20, v15
	v_mov_b32_e32 v22, v17
	v_lshl_add_u64 v[28:29], v[28:29], 0, v[122:123]
	s_mov_b64 s[2:3], -1
	s_waitcnt vmcnt(7)
	v_mov_b32_e32 v19, v248
	v_fmamk_f32 v13, v19, 0x39800000, v162
	v_rsq_f32_e32 v13, v13
	s_nop 0
	v_mul_f32_e32 v11, 0xbfb8aa3b, v13
	v_mul_f32_e32 v6, v6, v11
	v_mul_f32_e32 v19, v13, v13
	v_mul_f32_e32 v13, v7, v11
	v_mul_f32_e32 v15, v8, v11
	v_exp_f32_e32 v6, v6
	v_mul_f32_e32 v21, v2, v11
	v_exp_f32_e32 v13, v13
	v_exp_f32_e32 v15, v15
	v_mul_f32_e32 v17, v9, v11
	v_exp_f32_e32 v21, v21
	v_mul_f32_e32 v23, v3, v11
	v_exp_f32_e32 v17, v17
	v_mul_f32_e32 v25, v4, v11
	v_mul_f32_e32 v11, v5, v11
	v_exp_f32_e32 v23, v23
	v_add_f32_e32 v6, 1.0, v6
	v_exp_f32_e32 v11, v11
	v_add_f32_e32 v13, 1.0, v13
	v_add_f32_e32 v27, 1.0, v15
	v_rcp_f32_e32 v15, v6
	v_exp_f32_e32 v25, v25
	v_add_f32_e32 v31, 1.0, v21
	v_rcp_f32_e32 v21, v13
	v_add_f32_e32 v30, 1.0, v17
	v_rcp_f32_e32 v17, v27
	v_add_f32_e32 v32, 1.0, v23
	v_rcp_f32_e32 v23, v30
	v_add_f32_e32 v34, 1.0, v11
	v_rcp_f32_e32 v11, v31
	v_pk_mul_f32 v[14:15], v[18:19], v[14:15]
	v_mov_b32_e32 v18, v7
	v_add_f32_e32 v33, 1.0, v25
	v_rcp_f32_e32 v25, v32
	v_pk_mul_f32 v[6:7], v[18:19], v[20:21]
	v_mov_b32_e32 v18, v8
	v_rcp_f32_e32 v13, v33
	v_mul_f32_e32 v8, v6, v7
	v_pk_mul_f32 v[6:7], v[18:19], v[16:17]
	v_mov_b32_e32 v18, v9
	v_rcp_f32_e32 v27, v34
	v_mul_f32_e32 v9, v6, v7
	v_pk_mul_f32 v[6:7], v[18:19], v[22:23]
	v_mov_b32_e32 v18, v2
	v_mul_f32_e32 v14, v14, v15
	v_cvt_pk_bf16_f32 v2, v14, v8
	v_mul_f32_e32 v8, v6, v7
	v_pk_mul_f32 v[6:7], v[18:19], v[10:11]
	v_mov_b32_e32 v18, v3
	v_mul_f32_e32 v10, v6, v7
	v_pk_mul_f32 v[6:7], v[18:19], v[24:25]
	v_mov_b32_e32 v18, v4
	v_mul_f32_e32 v4, v6, v7
	v_pk_mul_f32 v[6:7], v[18:19], v[12:13]
	v_mov_b32_e32 v18, v5
	v_mul_f32_e32 v5, v6, v7
	v_pk_mul_f32 v[6:7], v[18:19], v[26:27]
	v_cvt_pk_bf16_f32 v3, v9, v8
	v_cvt_pk_bf16_f32 v4, v10, v4
	s_nop 0
	v_mul_f32_e32 v6, v6, v7
	v_cvt_pk_bf16_f32 v5, v5, v6
	global_store_dwordx4 v[28:29], v[2:5], off
	s_cbranch_vccnz .LBB0_1258
	s_andn2_b64 vcc, exec, s[0:1]
	s_cbranch_vccnz .LBB0_1257
	s_barrier
	s_branch .LBB0_1257

.LBB0_1542:
	v_lshl_add_u32 v142, s18, 8, v153
	v_ashrrev_i32_e32 v143, 31, v142
	v_lshl_add_u64 v[146:147], v[142:143], 2, s[4:5]
	global_load_dword v241, v[146:147], off
	global_load_dword v242, v[146:147], off offset:64
	global_load_dword v243, v[146:147], off offset:128
	global_load_dword v244, v[146:147], off offset:192
	global_load_dword v245, v[146:147], off offset:512
	global_load_dword v246, v[146:147], off offset:576
	global_load_dword v247, v[146:147], off offset:640
	global_load_dword v248, v[146:147], off offset:704
	v_mov_b32_e32 v174, v125
	v_mov_b32_e32 v166, v127
	v_mov_b32_e32 v164, v118
	v_mov_b32_e32 v168, v129
	v_lshl_or_b32 v162, s16, 7, v158
	v_mov_b64_e32 v[144:145], s[6:7]
	v_ashrrev_i32_e32 v163, 31, v162
	v_or_b32_e32 v178, 16, v142
	v_mov_b32_e32 v170, v122
	v_mov_b32_e32 v172, v123
	v_mad_i64_i32 v[176:177], s[2:3], v142, s50, v[144:145]
	v_lshlrev_b64 v[122:123], 1, v[162:163]
	v_ashrrev_i32_e32 v179, 31, v178
	v_lshl_add_u64 v[162:163], v[176:177], 0, v[122:123]
	v_lshl_add_u64 v[176:177], v[178:179], 2, s[4:5]
	s_andn2_b64 vcc, exec, s[20:21]
	s_waitcnt vmcnt(7)
	v_mov_b32_e32 v143, v241
	v_fmamk_f32 v125, v143, 0x39800000, v161
	v_rsq_f32_e32 v125, v125
	s_nop 0
	v_mul_f32_e32 v127, 0xbfb8aa3b, v125
	v_mul_f32_e32 v118, v118, v127
	v_mul_f32_e32 v165, v125, v125
	v_mul_f32_e32 v125, v119, v127
	v_mul_f32_e32 v129, v120, v127
	v_mul_f32_e32 v143, v121, v127
	v_mul_f32_e32 v167, v114, v127
	v_mul_f32_e32 v169, v115, v127
	v_mul_f32_e32 v171, v116, v127
	v_mul_f32_e32 v127, v117, v127
	v_exp_f32_e32 v118, v118
	v_exp_f32_e32 v125, v125
	v_exp_f32_e32 v127, v127
	v_exp_f32_e32 v129, v129
	v_exp_f32_e32 v167, v167
	v_exp_f32_e32 v143, v143
	v_exp_f32_e32 v169, v169
	v_add_f32_e32 v118, 1.0, v118
	v_exp_f32_e32 v171, v171
	v_add_f32_e32 v125, 1.0, v125
	v_add_f32_e32 v180, 1.0, v127
	v_rcp_f32_e32 v127, v118
	v_add_f32_e32 v129, 1.0, v129
	v_add_f32_e32 v173, 1.0, v167
	v_rcp_f32_e32 v167, v125
	v_add_f32_e32 v143, 1.0, v143
	v_rcp_f32_e32 v129, v129
	v_add_f32_e32 v175, 1.0, v169
	v_rcp_f32_e32 v169, v143
	v_add_f32_e32 v179, 1.0, v171
	v_rcp_f32_e32 v171, v173
	v_pk_mul_f32 v[126:127], v[164:165], v[126:127]
	v_mov_b32_e32 v164, v119
	v_rcp_f32_e32 v173, v175
	v_pk_mul_f32 v[118:119], v[164:165], v[166:167]
	v_mov_b32_e32 v164, v120
	v_rcp_f32_e32 v125, v179
	v_mul_f32_e32 v120, v118, v119
	v_pk_mul_f32 v[118:119], v[164:165], v[128:129]
	v_mov_b32_e32 v164, v121
	v_rcp_f32_e32 v175, v180
	v_mul_f32_e32 v121, v118, v119
	v_pk_mul_f32 v[118:119], v[164:165], v[168:169]
	v_mov_b32_e32 v164, v114
	v_mul_f32_e32 v126, v126, v127
	v_cvt_pk_bf16_f32 v114, v126, v120
	v_mul_f32_e32 v120, v118, v119
	v_pk_mul_f32 v[118:119], v[164:165], v[170:171]
	v_mov_b32_e32 v164, v115
	v_mul_f32_e32 v126, v118, v119
	v_pk_mul_f32 v[118:119], v[164:165], v[172:173]
	v_mov_b32_e32 v164, v116
	v_mul_f32_e32 v116, v118, v119
	v_pk_mul_f32 v[118:119], v[164:165], v[124:125]
	v_mov_b32_e32 v164, v117
	v_mul_f32_e32 v117, v118, v119
	v_pk_mul_f32 v[118:119], v[164:165], v[174:175]
	v_cvt_pk_bf16_f32 v115, v121, v120
	v_cvt_pk_bf16_f32 v116, v126, v116
	v_mov_b32_e32 v120, v107
	v_mul_f32_e32 v118, v118, v119
	v_cvt_pk_bf16_f32 v117, v117, v118
	global_store_dwordx4 v[162:163], v[114:117], off
	s_nop 0
	v_mov_b32_e32 v124, v109
	v_mov_b32_e32 v114, v102
	v_mov_b32_e32 v116, v111
	v_mov_b32_e32 v118, v113
	v_or_b32_e32 v126, 32, v142
	v_ashrrev_i32_e32 v127, 31, v126
	v_lshl_add_u64 v[162:163], v[126:127], 2, s[4:5]
	v_mad_i64_i32 v[128:129], s[2:3], v178, s50, v[144:145]
	v_lshl_add_u64 v[128:129], v[128:129], 0, v[122:123]
	s_waitcnt vmcnt(7)
	v_mov_b32_e32 v115, v242
	v_fmamk_f32 v107, v115, 0x39800000, v161
	v_rsq_f32_e32 v107, v107
	s_nop 0
	v_mul_f32_e32 v109, 0xbfb8aa3b, v107
	v_mul_f32_e32 v102, v102, v109
	v_mul_f32_e32 v115, v107, v107
	v_mul_f32_e32 v107, v103, v109
	v_mul_f32_e32 v111, v104, v109
	v_exp_f32_e32 v102, v102
	v_mul_f32_e32 v117, v98, v109
	v_exp_f32_e32 v107, v107
	v_exp_f32_e32 v111, v111
	v_mul_f32_e32 v113, v105, v109
	v_exp_f32_e32 v117, v117
	v_mul_f32_e32 v119, v99, v109
	v_exp_f32_e32 v113, v113
	v_exp_f32_e32 v119, v119
	v_add_f32_e32 v102, 1.0, v102
	v_mul_f32_e32 v121, v100, v109
	v_add_f32_e32 v107, 1.0, v107
	v_add_f32_e32 v125, 1.0, v111
	v_rcp_f32_e32 v111, v102
	v_mul_f32_e32 v109, v101, v109
	v_exp_f32_e32 v121, v121
	v_add_f32_e32 v143, 1.0, v117
	v_rcp_f32_e32 v117, v107
	v_exp_f32_e32 v109, v109
	v_add_f32_e32 v127, 1.0, v113
	v_rcp_f32_e32 v113, v125
	v_add_f32_e32 v164, 1.0, v119
	v_rcp_f32_e32 v119, v127
	v_rcp_f32_e32 v107, v143
	v_pk_mul_f32 v[110:111], v[114:115], v[110:111]
	v_mov_b32_e32 v114, v103
	v_add_f32_e32 v165, 1.0, v121
	v_rcp_f32_e32 v121, v164
	v_pk_mul_f32 v[102:103], v[114:115], v[116:117]
	v_mov_b32_e32 v114, v104
	v_add_f32_e32 v166, 1.0, v109
	v_rcp_f32_e32 v109, v165
	v_mul_f32_e32 v104, v102, v103
	v_pk_mul_f32 v[102:103], v[114:115], v[112:113]
	v_mov_b32_e32 v114, v105
	v_rcp_f32_e32 v125, v166
	v_mul_f32_e32 v105, v102, v103
	v_pk_mul_f32 v[102:103], v[114:115], v[118:119]
	v_mov_b32_e32 v114, v98
	v_mul_f32_e32 v110, v110, v111
	v_cvt_pk_bf16_f32 v98, v110, v104
	v_mul_f32_e32 v104, v102, v103
	v_pk_mul_f32 v[102:103], v[114:115], v[106:107]
	v_mov_b32_e32 v114, v99
	v_mul_f32_e32 v106, v102, v103
	v_pk_mul_f32 v[102:103], v[114:115], v[120:121]
	v_mov_b32_e32 v114, v100
	v_mul_f32_e32 v100, v102, v103
	v_pk_mul_f32 v[102:103], v[114:115], v[108:109]
	v_mov_b32_e32 v114, v101
	v_mul_f32_e32 v101, v102, v103
	v_pk_mul_f32 v[102:103], v[114:115], v[124:125]
	v_cvt_pk_bf16_f32 v99, v105, v104
	v_cvt_pk_bf16_f32 v100, v106, v100
	v_mov_b32_e32 v104, v91
	v_mul_f32_e32 v102, v102, v103
	v_cvt_pk_bf16_f32 v101, v101, v102
	global_store_dwordx4 v[128:129], v[98:101], off
	s_nop 0
	v_mov_b32_e32 v106, v93
	v_mov_b32_e32 v98, v86
	v_mov_b32_e32 v100, v95
	v_mov_b32_e32 v102, v97
	v_or_b32_e32 v108, 48, v142
	v_ashrrev_i32_e32 v109, 31, v108
	v_lshl_add_u64 v[112:113], v[108:109], 2, s[4:5]
	v_mad_i64_i32 v[110:111], s[2:3], v126, s50, v[144:145]
	v_lshl_add_u64 v[110:111], v[110:111], 0, v[122:123]
	s_waitcnt vmcnt(7)
	v_mov_b32_e32 v99, v243
	v_fmamk_f32 v91, v99, 0x39800000, v161
	v_rsq_f32_e32 v91, v91
	s_nop 0
	v_mul_f32_e32 v93, 0xbfb8aa3b, v91
	v_mul_f32_e32 v86, v86, v93
	v_mul_f32_e32 v99, v91, v91
	v_mul_f32_e32 v91, v87, v93
	v_mul_f32_e32 v95, v88, v93
	v_exp_f32_e32 v86, v86
	v_mul_f32_e32 v101, v82, v93
	v_exp_f32_e32 v91, v91
	v_exp_f32_e32 v95, v95
	v_mul_f32_e32 v97, v89, v93
	v_exp_f32_e32 v101, v101
	v_mul_f32_e32 v103, v83, v93
	v_exp_f32_e32 v97, v97
	v_exp_f32_e32 v103, v103
	v_add_f32_e32 v86, 1.0, v86
	v_mul_f32_e32 v105, v84, v93
	v_add_f32_e32 v91, 1.0, v91
	v_add_f32_e32 v107, 1.0, v95
	v_rcp_f32_e32 v95, v86
	v_mul_f32_e32 v93, v85, v93
	v_exp_f32_e32 v105, v105
	v_add_f32_e32 v114, 1.0, v101
	v_rcp_f32_e32 v101, v91
	v_exp_f32_e32 v93, v93
	v_add_f32_e32 v109, 1.0, v97
	v_rcp_f32_e32 v97, v107
	v_add_f32_e32 v115, 1.0, v103
	v_rcp_f32_e32 v103, v109
	v_rcp_f32_e32 v91, v114
	v_pk_mul_f32 v[94:95], v[98:99], v[94:95]
	v_mov_b32_e32 v98, v87
	v_add_f32_e32 v116, 1.0, v105
	v_rcp_f32_e32 v105, v115
	v_pk_mul_f32 v[86:87], v[98:99], v[100:101]
	v_mov_b32_e32 v98, v88
	v_add_f32_e32 v117, 1.0, v93
	v_rcp_f32_e32 v93, v116
	v_mul_f32_e32 v88, v86, v87
	v_pk_mul_f32 v[86:87], v[98:99], v[96:97]
	v_mov_b32_e32 v98, v89
	v_rcp_f32_e32 v107, v117
	v_mul_f32_e32 v89, v86, v87
	v_pk_mul_f32 v[86:87], v[98:99], v[102:103]
	v_mov_b32_e32 v98, v82
	v_mul_f32_e32 v94, v94, v95
	v_cvt_pk_bf16_f32 v82, v94, v88
	v_mul_f32_e32 v88, v86, v87
	v_pk_mul_f32 v[86:87], v[98:99], v[90:91]
	v_mov_b32_e32 v98, v83
	v_mul_f32_e32 v90, v86, v87
	v_pk_mul_f32 v[86:87], v[98:99], v[104:105]
	v_mov_b32_e32 v98, v84
	v_mul_f32_e32 v84, v86, v87
	v_pk_mul_f32 v[86:87], v[98:99], v[92:93]
	v_mov_b32_e32 v98, v85
	v_mul_f32_e32 v85, v86, v87
	v_pk_mul_f32 v[86:87], v[98:99], v[106:107]
	v_cvt_pk_bf16_f32 v83, v89, v88
	v_cvt_pk_bf16_f32 v84, v90, v84
	v_mov_b32_e32 v88, v75
	v_mul_f32_e32 v86, v86, v87
	v_cvt_pk_bf16_f32 v85, v85, v86
	global_store_dwordx4 v[110:111], v[82:85], off
	s_nop 0
	v_mov_b32_e32 v90, v77
	v_mov_b32_e32 v82, v70
	v_mov_b32_e32 v84, v79
	v_mov_b32_e32 v86, v81
	v_mad_i64_i32 v[92:93], s[2:3], v108, s50, v[144:145]
	v_lshl_add_u64 v[92:93], v[92:93], 0, v[122:123]
	s_waitcnt vmcnt(7)
	v_mov_b32_e32 v83, v244
	v_fmamk_f32 v75, v83, 0x39800000, v161
	v_rsq_f32_e32 v75, v75
	s_nop 0
	v_mul_f32_e32 v77, 0xbfb8aa3b, v75
	v_mul_f32_e32 v70, v70, v77
	v_mul_f32_e32 v83, v75, v75
	v_mul_f32_e32 v75, v71, v77
	v_mul_f32_e32 v79, v72, v77
	v_exp_f32_e32 v70, v70
	v_mul_f32_e32 v85, v66, v77
	v_exp_f32_e32 v75, v75
	v_exp_f32_e32 v79, v79
	v_mul_f32_e32 v81, v73, v77
	v_exp_f32_e32 v85, v85
	v_mul_f32_e32 v87, v67, v77
	v_exp_f32_e32 v81, v81
	v_exp_f32_e32 v87, v87
	v_add_f32_e32 v70, 1.0, v70
	v_mul_f32_e32 v89, v68, v77
	v_add_f32_e32 v75, 1.0, v75
	v_add_f32_e32 v91, 1.0, v79
	v_rcp_f32_e32 v79, v70
	v_mul_f32_e32 v77, v69, v77
	v_exp_f32_e32 v89, v89
	v_add_f32_e32 v95, 1.0, v85
	v_rcp_f32_e32 v85, v75
	v_exp_f32_e32 v77, v77
	v_add_f32_e32 v94, 1.0, v81
	v_rcp_f32_e32 v81, v91
	v_add_f32_e32 v96, 1.0, v87
	v_rcp_f32_e32 v87, v94
	v_rcp_f32_e32 v75, v95
	v_pk_mul_f32 v[78:79], v[82:83], v[78:79]
	v_mov_b32_e32 v82, v71
	v_add_f32_e32 v97, 1.0, v89
	v_rcp_f32_e32 v89, v96
	v_pk_mul_f32 v[70:71], v[82:83], v[84:85]
	v_mov_b32_e32 v82, v72
	v_add_f32_e32 v98, 1.0, v77
	v_rcp_f32_e32 v77, v97
	v_mul_f32_e32 v72, v70, v71
	v_pk_mul_f32 v[70:71], v[82:83], v[80:81]
	v_mov_b32_e32 v82, v73
	v_rcp_f32_e32 v91, v98
	v_mul_f32_e32 v73, v70, v71
	v_pk_mul_f32 v[70:71], v[82:83], v[86:87]
	v_mov_b32_e32 v82, v66
	v_mul_f32_e32 v78, v78, v79
	v_cvt_pk_bf16_f32 v66, v78, v72
	v_mul_f32_e32 v72, v70, v71
	v_pk_mul_f32 v[70:71], v[82:83], v[74:75]
	v_mov_b32_e32 v82, v67
	v_mul_f32_e32 v74, v70, v71
	v_pk_mul_f32 v[70:71], v[82:83], v[88:89]
	v_mov_b32_e32 v82, v68
	v_mul_f32_e32 v68, v70, v71
	v_pk_mul_f32 v[70:71], v[82:83], v[76:77]
	v_mov_b32_e32 v82, v69
	v_mul_f32_e32 v69, v70, v71
	v_pk_mul_f32 v[70:71], v[82:83], v[90:91]
	v_cvt_pk_bf16_f32 v67, v73, v72
	v_cvt_pk_bf16_f32 v68, v74, v68
	v_mov_b32_e32 v74, v61
	v_mul_f32_e32 v70, v70, v71
	v_cvt_pk_bf16_f32 v69, v69, v70
	global_store_dwordx4 v[92:93], v[66:69], off
	s_nop 0
	v_mov_b32_e32 v72, v59
	v_add_u32_e32 v59, 0x80, v142
	v_mad_i64_i32 v[76:77], s[2:3], v59, s50, v[144:145]
	v_mov_b32_e32 v66, v54
	v_mov_b32_e32 v68, v63
	v_mov_b32_e32 v70, v65
	v_lshl_add_u64 v[76:77], v[76:77], 0, v[122:123]
	s_waitcnt vmcnt(7)
	v_mov_b32_e32 v67, v245
	v_fmamk_f32 v61, v67, 0x39800000, v161
	v_rsq_f32_e32 v61, v61
	s_nop 0
	v_mul_f32_e32 v59, 0xbfb8aa3b, v61
	v_mul_f32_e32 v54, v54, v59
	v_mul_f32_e32 v67, v61, v61
	v_mul_f32_e32 v61, v55, v59
	v_mul_f32_e32 v63, v56, v59
	v_exp_f32_e32 v54, v54
	v_mul_f32_e32 v69, v50, v59
	v_exp_f32_e32 v61, v61
	v_exp_f32_e32 v63, v63
	v_mul_f32_e32 v65, v57, v59
	v_exp_f32_e32 v69, v69
	v_mul_f32_e32 v71, v51, v59
	v_exp_f32_e32 v65, v65
	v_mul_f32_e32 v73, v52, v59
	v_mul_f32_e32 v59, v53, v59
	v_exp_f32_e32 v71, v71
	v_add_f32_e32 v54, 1.0, v54
	v_exp_f32_e32 v59, v59
	v_add_f32_e32 v61, 1.0, v61
	v_add_f32_e32 v75, 1.0, v63
	v_rcp_f32_e32 v63, v54
	v_exp_f32_e32 v73, v73
	v_add_f32_e32 v79, 1.0, v69
	v_rcp_f32_e32 v69, v61
	v_add_f32_e32 v78, 1.0, v65
	v_rcp_f32_e32 v65, v75
	v_add_f32_e32 v80, 1.0, v71
	v_rcp_f32_e32 v71, v78
	v_add_f32_e32 v82, 1.0, v59
	v_rcp_f32_e32 v59, v79
	v_pk_mul_f32 v[62:63], v[66:67], v[62:63]
	v_mov_b32_e32 v66, v55
	v_add_f32_e32 v81, 1.0, v73
	v_rcp_f32_e32 v73, v80
	v_pk_mul_f32 v[54:55], v[66:67], v[68:69]
	v_mov_b32_e32 v66, v56
	v_rcp_f32_e32 v61, v81
	v_mul_f32_e32 v56, v54, v55
	v_pk_mul_f32 v[54:55], v[66:67], v[64:65]
	v_mov_b32_e32 v66, v57
	v_rcp_f32_e32 v75, v82
	v_mul_f32_e32 v57, v54, v55
	v_pk_mul_f32 v[54:55], v[66:67], v[70:71]
	v_mov_b32_e32 v66, v50
	v_mul_f32_e32 v62, v62, v63
	v_cvt_pk_bf16_f32 v50, v62, v56
	v_mul_f32_e32 v56, v54, v55
	v_pk_mul_f32 v[54:55], v[66:67], v[58:59]
	v_mov_b32_e32 v66, v51
	v_mul_f32_e32 v58, v54, v55
	v_pk_mul_f32 v[54:55], v[66:67], v[72:73]
	v_mov_b32_e32 v66, v52
	v_mul_f32_e32 v52, v54, v55
	v_pk_mul_f32 v[54:55], v[66:67], v[60:61]
	v_mov_b32_e32 v66, v53
	v_mul_f32_e32 v53, v54, v55
	v_pk_mul_f32 v[54:55], v[66:67], v[74:75]
	v_cvt_pk_bf16_f32 v51, v57, v56
	v_cvt_pk_bf16_f32 v52, v58, v52
	v_mov_b32_e32 v58, v45
	v_mul_f32_e32 v54, v54, v55
	v_cvt_pk_bf16_f32 v53, v53, v54
	global_store_dwordx4 v[76:77], v[50:53], off
	s_nop 0
	v_mov_b32_e32 v56, v43
	v_add_u32_e32 v43, 0x90, v142
	v_mad_i64_i32 v[60:61], s[2:3], v43, s50, v[144:145]
	v_mov_b32_e32 v50, v38
	v_mov_b32_e32 v52, v47
	v_mov_b32_e32 v54, v49
	v_lshl_add_u64 v[60:61], v[60:61], 0, v[122:123]
	s_waitcnt vmcnt(7)
	v_mov_b32_e32 v51, v246
	v_fmamk_f32 v45, v51, 0x39800000, v161
	v_rsq_f32_e32 v45, v45
	s_nop 0
	v_mul_f32_e32 v43, 0xbfb8aa3b, v45
	v_mul_f32_e32 v38, v38, v43
	v_mul_f32_e32 v51, v45, v45
	v_mul_f32_e32 v45, v39, v43
	v_mul_f32_e32 v47, v40, v43
	v_exp_f32_e32 v38, v38
	v_mul_f32_e32 v53, v34, v43
	v_exp_f32_e32 v45, v45
	v_exp_f32_e32 v47, v47
	v_mul_f32_e32 v49, v41, v43
	v_exp_f32_e32 v53, v53
	v_mul_f32_e32 v55, v35, v43
	v_exp_f32_e32 v49, v49
	v_mul_f32_e32 v57, v36, v43
	v_mul_f32_e32 v43, v37, v43
	v_exp_f32_e32 v55, v55
	v_add_f32_e32 v38, 1.0, v38
	v_exp_f32_e32 v43, v43
	v_add_f32_e32 v45, 1.0, v45
	v_add_f32_e32 v59, 1.0, v47
	v_rcp_f32_e32 v47, v38
	v_exp_f32_e32 v57, v57
	v_add_f32_e32 v63, 1.0, v53
	v_rcp_f32_e32 v53, v45
	v_add_f32_e32 v62, 1.0, v49
	v_rcp_f32_e32 v49, v59
	v_add_f32_e32 v64, 1.0, v55
	v_rcp_f32_e32 v55, v62
	v_add_f32_e32 v66, 1.0, v43
	v_rcp_f32_e32 v43, v63
	v_pk_mul_f32 v[46:47], v[50:51], v[46:47]
	v_mov_b32_e32 v50, v39
	v_add_f32_e32 v65, 1.0, v57
	v_rcp_f32_e32 v57, v64
	v_pk_mul_f32 v[38:39], v[50:51], v[52:53]
	v_mov_b32_e32 v50, v40
	v_rcp_f32_e32 v45, v65
	v_mul_f32_e32 v40, v38, v39
	v_pk_mul_f32 v[38:39], v[50:51], v[48:49]
	v_mov_b32_e32 v50, v41
	v_rcp_f32_e32 v59, v66
	v_mul_f32_e32 v41, v38, v39
	v_pk_mul_f32 v[38:39], v[50:51], v[54:55]
	v_mov_b32_e32 v50, v34
	v_mul_f32_e32 v46, v46, v47
	v_cvt_pk_bf16_f32 v34, v46, v40
	v_mul_f32_e32 v40, v38, v39
	v_pk_mul_f32 v[38:39], v[50:51], v[42:43]
	v_mov_b32_e32 v50, v35
	v_mul_f32_e32 v42, v38, v39
	v_pk_mul_f32 v[38:39], v[50:51], v[56:57]
	v_mov_b32_e32 v50, v36
	v_mul_f32_e32 v36, v38, v39
	v_pk_mul_f32 v[38:39], v[50:51], v[44:45]
	v_mov_b32_e32 v50, v37
	v_mul_f32_e32 v37, v38, v39
	v_pk_mul_f32 v[38:39], v[50:51], v[58:59]
	v_cvt_pk_bf16_f32 v35, v41, v40
	v_cvt_pk_bf16_f32 v36, v42, v36
	v_mov_b32_e32 v42, v29
	v_mul_f32_e32 v38, v38, v39
	v_cvt_pk_bf16_f32 v37, v37, v38
	global_store_dwordx4 v[60:61], v[34:37], off
	s_nop 0
	v_mov_b32_e32 v40, v27
	v_add_u32_e32 v27, 0xa0, v142
	v_mad_i64_i32 v[44:45], s[2:3], v27, s50, v[144:145]
	v_mov_b32_e32 v34, v22
	v_mov_b32_e32 v36, v31
	v_mov_b32_e32 v38, v33
	v_lshl_add_u64 v[44:45], v[44:45], 0, v[122:123]
	s_waitcnt vmcnt(7)
	v_mov_b32_e32 v35, v247
	v_fmamk_f32 v29, v35, 0x39800000, v161
	v_rsq_f32_e32 v29, v29
	s_nop 0
	v_mul_f32_e32 v27, 0xbfb8aa3b, v29
	v_mul_f32_e32 v22, v22, v27
	v_mul_f32_e32 v35, v29, v29
	v_mul_f32_e32 v29, v23, v27
	v_mul_f32_e32 v31, v24, v27
	v_exp_f32_e32 v22, v22
	v_mul_f32_e32 v37, v18, v27
	v_exp_f32_e32 v29, v29
	v_exp_f32_e32 v31, v31
	v_mul_f32_e32 v33, v25, v27
	v_exp_f32_e32 v37, v37
	v_mul_f32_e32 v39, v19, v27
	v_exp_f32_e32 v33, v33
	v_mul_f32_e32 v41, v20, v27
	v_mul_f32_e32 v27, v21, v27
	v_exp_f32_e32 v39, v39
	v_add_f32_e32 v22, 1.0, v22
	v_exp_f32_e32 v27, v27
	v_add_f32_e32 v29, 1.0, v29
	v_add_f32_e32 v43, 1.0, v31
	v_rcp_f32_e32 v31, v22
	v_exp_f32_e32 v41, v41
	v_add_f32_e32 v47, 1.0, v37
	v_rcp_f32_e32 v37, v29
	v_add_f32_e32 v46, 1.0, v33
	v_rcp_f32_e32 v33, v43
	v_add_f32_e32 v48, 1.0, v39
	v_rcp_f32_e32 v39, v46
	v_add_f32_e32 v50, 1.0, v27
	v_rcp_f32_e32 v27, v47
	v_pk_mul_f32 v[30:31], v[34:35], v[30:31]
	v_mov_b32_e32 v34, v23
	v_add_f32_e32 v49, 1.0, v41
	v_rcp_f32_e32 v41, v48
	v_pk_mul_f32 v[22:23], v[34:35], v[36:37]
	v_mov_b32_e32 v34, v24
	v_rcp_f32_e32 v29, v49
	v_mul_f32_e32 v24, v22, v23
	v_pk_mul_f32 v[22:23], v[34:35], v[32:33]
	v_mov_b32_e32 v34, v25
	v_rcp_f32_e32 v43, v50
	v_mul_f32_e32 v25, v22, v23
	v_pk_mul_f32 v[22:23], v[34:35], v[38:39]
	v_mov_b32_e32 v34, v18
	v_mul_f32_e32 v30, v30, v31
	v_cvt_pk_bf16_f32 v18, v30, v24
	v_mul_f32_e32 v24, v22, v23
	v_pk_mul_f32 v[22:23], v[34:35], v[26:27]
	v_mov_b32_e32 v34, v19
	v_mul_f32_e32 v26, v22, v23
	v_pk_mul_f32 v[22:23], v[34:35], v[40:41]
	v_mov_b32_e32 v34, v20
	v_mul_f32_e32 v20, v22, v23
	v_pk_mul_f32 v[22:23], v[34:35], v[28:29]
	v_mov_b32_e32 v34, v21
	v_mul_f32_e32 v21, v22, v23
	v_pk_mul_f32 v[22:23], v[34:35], v[42:43]
	v_cvt_pk_bf16_f32 v19, v25, v24
	v_cvt_pk_bf16_f32 v20, v26, v20
	v_mov_b32_e32 v26, v13
	v_mul_f32_e32 v22, v22, v23
	v_cvt_pk_bf16_f32 v21, v21, v22
	global_store_dwordx4 v[44:45], v[18:21], off
	s_nop 0
	v_mov_b32_e32 v24, v11
	v_add_u32_e32 v11, 0xb0, v142
	v_mad_i64_i32 v[28:29], s[2:3], v11, s50, v[144:145]
	v_mov_b32_e32 v18, v6
	v_mov_b32_e32 v20, v15
	v_mov_b32_e32 v22, v17
	v_lshl_add_u64 v[28:29], v[28:29], 0, v[122:123]
	s_mov_b64 s[2:3], -1
	s_waitcnt vmcnt(7)
	v_mov_b32_e32 v19, v248
	v_fmamk_f32 v13, v19, 0x39800000, v161
	v_rsq_f32_e32 v13, v13
	s_nop 0
	v_mul_f32_e32 v11, 0xbfb8aa3b, v13
	v_mul_f32_e32 v6, v6, v11
	v_mul_f32_e32 v19, v13, v13
	v_mul_f32_e32 v13, v7, v11
	v_mul_f32_e32 v15, v8, v11
	v_exp_f32_e32 v6, v6
	v_mul_f32_e32 v21, v2, v11
	v_exp_f32_e32 v13, v13
	v_exp_f32_e32 v15, v15
	v_mul_f32_e32 v17, v9, v11
	v_exp_f32_e32 v21, v21
	v_mul_f32_e32 v23, v3, v11
	v_exp_f32_e32 v17, v17
	v_mul_f32_e32 v25, v4, v11
	v_mul_f32_e32 v11, v5, v11
	v_exp_f32_e32 v23, v23
	v_add_f32_e32 v6, 1.0, v6
	v_exp_f32_e32 v11, v11
	v_add_f32_e32 v13, 1.0, v13
	v_add_f32_e32 v27, 1.0, v15
	v_rcp_f32_e32 v15, v6
	v_exp_f32_e32 v25, v25
	v_add_f32_e32 v31, 1.0, v21
	v_rcp_f32_e32 v21, v13
	v_add_f32_e32 v30, 1.0, v17
	v_rcp_f32_e32 v17, v27
	v_add_f32_e32 v32, 1.0, v23
	v_rcp_f32_e32 v23, v30
	v_add_f32_e32 v34, 1.0, v11
	v_rcp_f32_e32 v11, v31
	v_pk_mul_f32 v[14:15], v[18:19], v[14:15]
	v_mov_b32_e32 v18, v7
	v_add_f32_e32 v33, 1.0, v25
	v_rcp_f32_e32 v25, v32
	v_pk_mul_f32 v[6:7], v[18:19], v[20:21]
	v_mov_b32_e32 v18, v8
	v_rcp_f32_e32 v13, v33
	v_mul_f32_e32 v8, v6, v7
	v_pk_mul_f32 v[6:7], v[18:19], v[16:17]
	v_mov_b32_e32 v18, v9
	v_rcp_f32_e32 v27, v34
	v_mul_f32_e32 v9, v6, v7
	v_pk_mul_f32 v[6:7], v[18:19], v[22:23]
	v_mov_b32_e32 v18, v2
	v_mul_f32_e32 v14, v14, v15
	v_cvt_pk_bf16_f32 v2, v14, v8
	v_mul_f32_e32 v8, v6, v7
	v_pk_mul_f32 v[6:7], v[18:19], v[10:11]
	v_mov_b32_e32 v18, v3
	v_mul_f32_e32 v10, v6, v7
	v_pk_mul_f32 v[6:7], v[18:19], v[24:25]
	v_mov_b32_e32 v18, v4
	v_mul_f32_e32 v4, v6, v7
	v_pk_mul_f32 v[6:7], v[18:19], v[12:13]
	v_mov_b32_e32 v18, v5
	v_mul_f32_e32 v5, v6, v7
	v_pk_mul_f32 v[6:7], v[18:19], v[26:27]
	v_cvt_pk_bf16_f32 v3, v9, v8
	v_cvt_pk_bf16_f32 v4, v10, v4
	s_nop 0
	v_mul_f32_e32 v6, v6, v7
	v_cvt_pk_bf16_f32 v5, v5, v6
	global_store_dwordx4 v[28:29], v[2:5], off
	s_cbranch_vccnz .LBB0_1464
	s_andn2_b64 vcc, exec, s[0:1]
	s_cbranch_vccnz .LBB0_1463
	s_barrier
	s_branch .LBB0_1463

.LBB0_1553:
	v_lshl_add_u32 v66, s2, 7, v68
	v_ashrrev_i32_e32 v67, 31, v66
	v_lshl_add_u64 v[70:71], v[66:67], 2, s[4:5]
	global_load_dword v241, v[70:71], off
	global_load_dword v242, v[70:71], off offset:64
	global_load_dword v243, v[70:71], off offset:256
	global_load_dword v244, v[70:71], off offset:320
	v_mov_b32_e32 v67, 0x358637bd
	v_mov_b32_e32 v82, v61
	v_mov_b32_e32 v74, v63
	v_lshl_or_b32 v75, s0, 7, v148
	v_mov_b32_e32 v72, v54
	v_mov_b32_e32 v76, v65
	v_mov_b32_e32 v78, v58
	v_or_b32_e32 v58, s1, v75
	v_or_b32_e32 v86, 16, v66
	v_ashrrev_i32_e32 v87, 31, v86
	v_lshl_add_u64 v[88:89], v[86:87], 2, s[4:5]
	v_mov_b32_e32 v80, v59
	s_movk_i32 s0, 0x5600
	v_mov_b64_e32 v[68:69], s[6:7]
	v_mov_b32_e32 v59, 0
	v_mad_i64_i32 v[84:85], s[2:3], v66, s0, v[68:69]
	v_lshlrev_b32_e32 v58, 1, v58
	v_lshl_add_u64 v[84:85], v[84:85], 0, v[58:59]
	s_waitcnt vmcnt(3)
	v_mov_b32_e32 v73, v241
	v_fmamk_f32 v61, v73, 0x39800000, v67
	v_rsq_f32_e32 v61, v61
	s_nop 0
	v_mul_f32_e32 v63, 0xbfb8aa3b, v61
	v_mul_f32_e32 v54, v54, v63
	v_mul_f32_e32 v73, v61, v61
	v_mul_f32_e32 v61, v55, v63
	v_mul_f32_e32 v65, v56, v63
	v_mul_f32_e32 v75, v57, v63
	v_mul_f32_e32 v77, v50, v63
	v_mul_f32_e32 v79, v51, v63
	v_mul_f32_e32 v81, v52, v63
	v_mul_f32_e32 v63, v53, v63
	v_exp_f32_e32 v54, v54
	v_exp_f32_e32 v61, v61
	v_exp_f32_e32 v63, v63
	v_exp_f32_e32 v65, v65
	v_exp_f32_e32 v75, v75
	v_exp_f32_e32 v77, v77
	v_add_f32_e32 v54, 1.0, v54
	v_exp_f32_e32 v79, v79
	v_add_f32_e32 v61, 1.0, v61
	v_add_f32_e32 v92, 1.0, v63
	v_rcp_f32_e32 v63, v54
	v_exp_f32_e32 v81, v81
	v_add_f32_e32 v65, 1.0, v65
	v_add_f32_e32 v83, 1.0, v75
	v_rcp_f32_e32 v75, v61
	v_rcp_f32_e32 v65, v65
	v_add_f32_e32 v87, 1.0, v77
	v_rcp_f32_e32 v77, v83
	v_add_f32_e32 v90, 1.0, v79
	v_rcp_f32_e32 v79, v87
	v_pk_mul_f32 v[62:63], v[72:73], v[62:63]
	v_mov_b32_e32 v72, v55
	v_add_f32_e32 v91, 1.0, v81
	v_rcp_f32_e32 v81, v90
	v_pk_mul_f32 v[54:55], v[72:73], v[74:75]
	v_mov_b32_e32 v72, v56
	v_rcp_f32_e32 v61, v91
	v_mul_f32_e32 v56, v54, v55
	v_pk_mul_f32 v[54:55], v[72:73], v[64:65]
	v_mov_b32_e32 v72, v57
	v_rcp_f32_e32 v83, v92
	v_mul_f32_e32 v57, v54, v55
	v_pk_mul_f32 v[54:55], v[72:73], v[76:77]
	v_mov_b32_e32 v72, v50
	v_mul_f32_e32 v62, v62, v63
	v_cvt_pk_bf16_f32 v50, v62, v56
	v_mul_f32_e32 v56, v54, v55
	v_pk_mul_f32 v[54:55], v[72:73], v[78:79]
	v_mov_b32_e32 v72, v51
	v_mul_f32_e32 v62, v54, v55
	v_pk_mul_f32 v[54:55], v[72:73], v[80:81]
	v_mov_b32_e32 v72, v52
	v_mul_f32_e32 v52, v54, v55
	v_pk_mul_f32 v[54:55], v[72:73], v[60:61]
	v_mov_b32_e32 v72, v53
	v_mul_f32_e32 v53, v54, v55
	v_pk_mul_f32 v[54:55], v[72:73], v[82:83]
	v_cvt_pk_bf16_f32 v51, v57, v56
	v_cvt_pk_bf16_f32 v52, v62, v52
	v_mov_b32_e32 v56, v43
	v_mul_f32_e32 v54, v54, v55
	v_cvt_pk_bf16_f32 v53, v53, v54
	global_store_dwordx4 v[84:85], v[50:53], off
	s_nop 0
	v_mov_b32_e32 v60, v45
	v_mov_b32_e32 v50, v38
	v_mov_b32_e32 v52, v47
	v_mov_b32_e32 v54, v49
	v_mad_i64_i32 v[62:63], s[2:3], v86, s0, v[68:69]
	v_lshl_add_u64 v[62:63], v[62:63], 0, v[58:59]
	s_waitcnt vmcnt(3)
	v_mov_b32_e32 v51, v242
	v_fmamk_f32 v43, v51, 0x39800000, v67
	v_rsq_f32_e32 v43, v43
	s_nop 0
	v_mul_f32_e32 v45, 0xbfb8aa3b, v43
	v_mul_f32_e32 v38, v38, v45
	v_mul_f32_e32 v51, v43, v43
	v_mul_f32_e32 v43, v39, v45
	v_mul_f32_e32 v47, v40, v45
	v_exp_f32_e32 v38, v38
	v_mul_f32_e32 v53, v34, v45
	v_exp_f32_e32 v43, v43
	v_exp_f32_e32 v47, v47
	v_mul_f32_e32 v49, v41, v45
	v_exp_f32_e32 v53, v53
	v_mul_f32_e32 v55, v35, v45
	v_exp_f32_e32 v49, v49
	v_exp_f32_e32 v55, v55
	v_add_f32_e32 v38, 1.0, v38
	v_mul_f32_e32 v57, v36, v45
	v_add_f32_e32 v43, 1.0, v43
	v_add_f32_e32 v61, 1.0, v47
	v_rcp_f32_e32 v47, v38
	v_mul_f32_e32 v45, v37, v45
	v_exp_f32_e32 v57, v57
	v_add_f32_e32 v65, 1.0, v53
	v_rcp_f32_e32 v53, v43
	v_exp_f32_e32 v45, v45
	v_add_f32_e32 v64, 1.0, v49
	v_rcp_f32_e32 v49, v61
	v_add_f32_e32 v72, 1.0, v55
	v_rcp_f32_e32 v55, v64
	v_rcp_f32_e32 v43, v65
	v_pk_mul_f32 v[46:47], v[50:51], v[46:47]
	v_mov_b32_e32 v50, v39
	v_add_f32_e32 v73, 1.0, v57
	v_rcp_f32_e32 v57, v72
	v_pk_mul_f32 v[38:39], v[50:51], v[52:53]
	v_mov_b32_e32 v50, v40
	v_add_f32_e32 v74, 1.0, v45
	v_rcp_f32_e32 v45, v73
	v_mul_f32_e32 v40, v38, v39
	v_pk_mul_f32 v[38:39], v[50:51], v[48:49]
	v_mov_b32_e32 v50, v41
	v_rcp_f32_e32 v61, v74
	v_mul_f32_e32 v41, v38, v39
	v_pk_mul_f32 v[38:39], v[50:51], v[54:55]
	v_mov_b32_e32 v50, v34
	v_mul_f32_e32 v46, v46, v47
	v_cvt_pk_bf16_f32 v34, v46, v40
	v_mul_f32_e32 v40, v38, v39
	v_pk_mul_f32 v[38:39], v[50:51], v[42:43]
	v_mov_b32_e32 v50, v35
	v_mul_f32_e32 v42, v38, v39
	v_pk_mul_f32 v[38:39], v[50:51], v[56:57]
	v_mov_b32_e32 v50, v36
	v_mul_f32_e32 v36, v38, v39
	v_pk_mul_f32 v[38:39], v[50:51], v[44:45]
	v_mov_b32_e32 v50, v37
	v_mul_f32_e32 v37, v38, v39
	v_pk_mul_f32 v[38:39], v[50:51], v[60:61]
	v_cvt_pk_bf16_f32 v35, v41, v40
	v_cvt_pk_bf16_f32 v36, v42, v36
	v_mov_b32_e32 v42, v29
	v_mul_f32_e32 v38, v38, v39
	v_cvt_pk_bf16_f32 v37, v37, v38
	global_store_dwordx4 v[62:63], v[34:37], off
	s_nop 0
	v_mov_b32_e32 v40, v27
	v_add_u32_e32 v27, 64, v66
	v_mad_i64_i32 v[44:45], s[2:3], v27, s0, v[68:69]
	v_mov_b32_e32 v34, v22
	v_mov_b32_e32 v36, v31
	v_mov_b32_e32 v38, v33
	v_lshl_add_u64 v[44:45], v[44:45], 0, v[58:59]
	s_waitcnt vmcnt(3)
	v_mov_b32_e32 v35, v243
	v_fmamk_f32 v29, v35, 0x39800000, v67
	v_rsq_f32_e32 v29, v29
	s_nop 0
	v_mul_f32_e32 v27, 0xbfb8aa3b, v29
	v_mul_f32_e32 v22, v22, v27
	v_mul_f32_e32 v35, v29, v29
	v_mul_f32_e32 v29, v23, v27
	v_mul_f32_e32 v31, v24, v27
	v_exp_f32_e32 v22, v22
	v_mul_f32_e32 v37, v18, v27
	v_exp_f32_e32 v29, v29
	v_exp_f32_e32 v31, v31
	v_mul_f32_e32 v33, v25, v27
	v_exp_f32_e32 v37, v37
	v_mul_f32_e32 v39, v19, v27
	v_exp_f32_e32 v33, v33
	v_mul_f32_e32 v41, v20, v27
	v_mul_f32_e32 v27, v21, v27
	v_exp_f32_e32 v39, v39
	v_add_f32_e32 v22, 1.0, v22
	v_exp_f32_e32 v27, v27
	v_add_f32_e32 v29, 1.0, v29
	v_add_f32_e32 v43, 1.0, v31
	v_rcp_f32_e32 v31, v22
	v_exp_f32_e32 v41, v41
	v_add_f32_e32 v47, 1.0, v37
	v_rcp_f32_e32 v37, v29
	v_add_f32_e32 v46, 1.0, v33
	v_rcp_f32_e32 v33, v43
	v_add_f32_e32 v48, 1.0, v39
	v_rcp_f32_e32 v39, v46
	v_add_f32_e32 v50, 1.0, v27
	v_rcp_f32_e32 v27, v47
	v_pk_mul_f32 v[30:31], v[34:35], v[30:31]
	v_mov_b32_e32 v34, v23
	v_add_f32_e32 v49, 1.0, v41
	v_rcp_f32_e32 v41, v48
	v_pk_mul_f32 v[22:23], v[34:35], v[36:37]
	v_mov_b32_e32 v34, v24
	v_rcp_f32_e32 v29, v49
	v_mul_f32_e32 v24, v22, v23
	v_pk_mul_f32 v[22:23], v[34:35], v[32:33]
	v_mov_b32_e32 v34, v25
	v_rcp_f32_e32 v43, v50
	v_mul_f32_e32 v25, v22, v23
	v_pk_mul_f32 v[22:23], v[34:35], v[38:39]
	v_mov_b32_e32 v34, v18
	v_mul_f32_e32 v30, v30, v31
	v_cvt_pk_bf16_f32 v18, v30, v24
	v_mul_f32_e32 v24, v22, v23
	v_pk_mul_f32 v[22:23], v[34:35], v[26:27]
	v_mov_b32_e32 v34, v19
	v_mul_f32_e32 v26, v22, v23
	v_pk_mul_f32 v[22:23], v[34:35], v[40:41]
	v_mov_b32_e32 v34, v20
	v_mul_f32_e32 v20, v22, v23
	v_pk_mul_f32 v[22:23], v[34:35], v[28:29]
	v_mov_b32_e32 v34, v21
	v_mul_f32_e32 v21, v22, v23
	v_pk_mul_f32 v[22:23], v[34:35], v[42:43]
	v_cvt_pk_bf16_f32 v19, v25, v24
	v_cvt_pk_bf16_f32 v20, v26, v20
	v_mov_b32_e32 v26, v13
	v_mul_f32_e32 v22, v22, v23
	v_cvt_pk_bf16_f32 v21, v21, v22
	global_store_dwordx4 v[44:45], v[18:21], off
	s_nop 0
	v_mov_b32_e32 v24, v11
	v_add_u32_e32 v11, 0x50, v66
	v_mad_i64_i32 v[28:29], s[0:1], v11, s0, v[68:69]
	v_mov_b32_e32 v18, v6
	v_mov_b32_e32 v20, v15
	v_mov_b32_e32 v22, v17
	v_lshl_add_u64 v[28:29], v[28:29], 0, v[58:59]
	s_waitcnt vmcnt(3)
	v_mov_b32_e32 v19, v244
	v_fmac_f32_e32 v67, 0x39800000, v19
	v_rsq_f32_e32 v13, v67
	s_nop 0
	v_mul_f32_e32 v11, 0xbfb8aa3b, v13
	v_mul_f32_e32 v6, v6, v11
	v_mul_f32_e32 v19, v13, v13
	v_mul_f32_e32 v13, v7, v11
	v_mul_f32_e32 v15, v8, v11
	v_exp_f32_e32 v6, v6
	v_mul_f32_e32 v21, v2, v11
	v_exp_f32_e32 v13, v13
	v_exp_f32_e32 v15, v15
	v_mul_f32_e32 v17, v9, v11
	v_exp_f32_e32 v21, v21
	v_mul_f32_e32 v23, v3, v11
	v_exp_f32_e32 v17, v17
	v_mul_f32_e32 v25, v4, v11
	v_mul_f32_e32 v11, v5, v11
	v_exp_f32_e32 v23, v23
	v_add_f32_e32 v6, 1.0, v6
	v_exp_f32_e32 v11, v11
	v_add_f32_e32 v13, 1.0, v13
	v_add_f32_e32 v27, 1.0, v15
	v_rcp_f32_e32 v15, v6
	v_exp_f32_e32 v25, v25
	v_add_f32_e32 v31, 1.0, v21
	v_rcp_f32_e32 v21, v13
	v_add_f32_e32 v30, 1.0, v17
	v_rcp_f32_e32 v17, v27
	v_add_f32_e32 v32, 1.0, v23
	v_rcp_f32_e32 v23, v30
	v_add_f32_e32 v34, 1.0, v11
	v_rcp_f32_e32 v11, v31
	v_pk_mul_f32 v[14:15], v[18:19], v[14:15]
	v_mov_b32_e32 v18, v7
	v_add_f32_e32 v33, 1.0, v25
	v_rcp_f32_e32 v25, v32
	v_pk_mul_f32 v[6:7], v[18:19], v[20:21]
	v_mov_b32_e32 v18, v8
	v_rcp_f32_e32 v13, v33
	v_mul_f32_e32 v8, v6, v7
	v_pk_mul_f32 v[6:7], v[18:19], v[16:17]
	v_mov_b32_e32 v18, v9
	v_rcp_f32_e32 v27, v34
	v_mul_f32_e32 v9, v6, v7
	v_pk_mul_f32 v[6:7], v[18:19], v[22:23]
	v_mov_b32_e32 v18, v2
	v_mul_f32_e32 v14, v14, v15
	v_cvt_pk_bf16_f32 v2, v14, v8
	v_mul_f32_e32 v8, v6, v7
	v_pk_mul_f32 v[6:7], v[18:19], v[10:11]
	v_mov_b32_e32 v18, v3
	v_mul_f32_e32 v10, v6, v7
	v_pk_mul_f32 v[6:7], v[18:19], v[24:25]
	v_mov_b32_e32 v18, v4
	v_cvt_pk_bf16_f32 v3, v9, v8
	v_mul_f32_e32 v8, v6, v7
	v_pk_mul_f32 v[6:7], v[18:19], v[12:13]
	v_mov_b32_e32 v18, v5
	v_pk_mul_f32 v[4:5], v[18:19], v[26:27]
	v_mul_f32_e32 v6, v6, v7
	v_mul_f32_e32 v5, v4, v5
	v_cvt_pk_bf16_f32 v4, v10, v8
	v_cvt_pk_bf16_f32 v5, v6, v5
	global_store_dwordx4 v[28:29], v[2:5], off
	s_waitcnt vmcnt(0)
	s_barrier

	.amdhsa_kernel _Z8skel_fwd4Args
		.amdhsa_group_segment_fixed_size 0
		.amdhsa_private_segment_fixed_size 0
		.amdhsa_kernarg_size 448
		.amdhsa_user_sgpr_count 2
		.amdhsa_user_sgpr_dispatch_ptr 0
		.amdhsa_user_sgpr_queue_ptr 0
		.amdhsa_user_sgpr_kernarg_segment_ptr 1
		.amdhsa_user_sgpr_dispatch_id 0
		.amdhsa_user_sgpr_kernarg_preload_length 0
		.amdhsa_user_sgpr_kernarg_preload_offset 0
		.amdhsa_user_sgpr_private_segment_size 0
		.amdhsa_uses_dynamic_stack 0
		.amdhsa_enable_private_segment 0
		.amdhsa_system_sgpr_workgroup_id_x 1
		.amdhsa_system_sgpr_workgroup_id_y 0
		.amdhsa_system_sgpr_workgroup_id_z 0
		.amdhsa_system_sgpr_workgroup_info 0
		.amdhsa_system_vgpr_workitem_id 0
		.amdhsa_next_free_vgpr 249
		.amdhsa_next_free_sgpr 98
		.amdhsa_accum_offset 252
		.amdhsa_reserve_vcc 1
		.amdhsa_float_round_mode_32 0
		.amdhsa_float_round_mode_16_64 0
		.amdhsa_float_denorm_mode_32 3
		.amdhsa_float_denorm_mode_16_64 3
		.amdhsa_dx10_clamp 1
		.amdhsa_ieee_mode 1
		.amdhsa_fp16_overflow 0
		.amdhsa_tg_split 0
		.amdhsa_exception_fp_ieee_invalid_op 0
		.amdhsa_exception_fp_denorm_src 0
		.amdhsa_exception_fp_ieee_div_zero 0
		.amdhsa_exception_fp_ieee_overflow 0
		.amdhsa_exception_fp_ieee_underflow 0
		.amdhsa_exception_fp_ieee_inexact 0
		.amdhsa_exception_int_div_zero 0
	.end_amdhsa_kernel

amdhsa.kernels:
  - .agpr_count:     0
    .args:
      - .offset:         0
        .size:           192
        .value_kind:     by_value
      - .offset:         192
        .size:           4
        .value_kind:     hidden_block_count_x
      - .offset:         196
        .size:           4
        .value_kind:     hidden_block_count_y
      - .offset:         200
        .size:           4
        .value_kind:     hidden_block_count_z
      - .offset:         204
        .size:           2
        .value_kind:     hidden_group_size_x
      - .offset:         206
        .size:           2
        .value_kind:     hidden_group_size_y
      - .offset:         208
        .size:           2
        .value_kind:     hidden_group_size_z
      - .offset:         210
        .size:           2
        .value_kind:     hidden_remainder_x
      - .offset:         212
        .size:           2
        .value_kind:     hidden_remainder_y
      - .offset:         214
        .size:           2
        .value_kind:     hidden_remainder_z
      - .offset:         232
        .size:           8
        .value_kind:     hidden_global_offset_x
      - .offset:         240
        .size:           8
        .value_kind:     hidden_global_offset_y
      - .offset:         248
        .size:           8
        .value_kind:     hidden_global_offset_z
      - .offset:         256
        .size:           2
        .value_kind:     hidden_grid_dims
      - .offset:         312
        .size:           4
        .value_kind:     hidden_dynamic_lds_size
    .group_segment_fixed_size: 0
    .kernarg_segment_align: 8
    .kernarg_segment_size: 448
    .language:       OpenCL C
    .language_version:
      - 2
      - 0
    .max_flat_workgroup_size: 512
    .name:           _Z8skel_fwd4Args
    .private_segment_fixed_size: 0
    .sgpr_count:     104
    .sgpr_spill_count: 29
    .symbol:         _Z8skel_fwd4Args.kd
    .uniform_work_group_size: 1
    .uses_dynamic_stack: false
    .vgpr_count:     249
    .vgpr_spill_count: 0
    .wavefront_size: 64
